# byte-phase placement: every K-loop MFMA run starts at an address 0 mod 8 (15 s_nop pads)
# baseline (speedup 1.0000x reference)
; #define STAGE(bufoff, GB) do { const char* g_ = (GB); \
;         _Pragma("unroll") for (int i_ = 0; i_ < 2; ++i_) __builtin_amdgcn_global_load_lds((const unsigned*)(g_ + voff[i_]), (LAS3 unsigned*)(L + (bufoff) + stoff + i_ * 8192), 16, 0, 0); } while (0)
; #define LDA(dst, b, h) do { _Pragma("unroll") for (int m = 0; m < 4; ++m) _Pragma("unroll") for (int k = 0; k < 2; ++k) dst[m][k] = *(const LAS3 bf16x8*)(L + SA(b, h) + aoff + m * 2048 + k * 1024); } while (0)
; #define LDB(dst, b, h) do { _Pragma("unroll") for (int n = 0; n < 2; ++n) _Pragma("unroll") for (int k = 0; k < 2; ++k) dst[n][k] = *(const LAS3 bf16x8*)(L + SB(b, h) + boff + n * 2048 + k * 1024); } while (0)
; #define WAIT_V(n) asm volatile("s_waitcnt vmcnt(" #n ")" ::: "memory")
; #define WAIT_L(n) asm volatile("s_waitcnt lgkmcnt(" #n ")" ::: "memory")
; #define BAR __builtin_amdgcn_s_barrier()
; #define SCHED __builtin_amdgcn_sched_barrier(0)
; template <int EPI>
; DI void gemm_phase(const bf16_t* __restrict__ A, const bf16_t* __restrict__ Bt, const int K, const int N, const Params& p, const int layer_j, char* lds) {
;     ...
;             LDA(At, 0, 1); STAGE(SB(0, 0), b2); STAGE(SB(0, 1), b2 + hstep); STAGE(SA(0, 0), a2);
;             WAIT_V(8); WAIT_L(0); BAR; MMA(1, 0, At, B0); MMA(1, 1, At, B1); BAR; SCHED;
;             LDB(B0, 1, 0); LDB(B1, 1, 1); SCHED; LDA(At, 1, 0); STAGE(SA(0, 1), a2 + hstep);
;             WAIT_V(8); WAIT_L(0); BAR; MMA(0, 0, At, B0); MMA(0, 1, At, B1); BAR; SCHED;
.Lskipw_ffn_1:
	s_waitcnt lgkmcnt(0)
	s_barrier
	s_setprio 1
	s_waitcnt lgkmcnt(0)
	s_nop 0
	v_mfma_f32_16x16x32_bf16 v[62:65], v[152:155], v[184:187], v[62:65]
	v_mfma_f32_16x16x32_bf16 v[54:57], v[160:163], v[184:187], v[54:57]
	v_mfma_f32_16x16x32_bf16 v[46:49], v[152:155], v[204:207], v[46:49]
	v_mfma_f32_16x16x32_bf16 v[38:41], v[160:163], v[204:207], v[38:41]
	v_mfma_f32_16x16x32_bf16 v[24:27], v[152:155], v[212:215], v[24:27]
	v_mfma_f32_16x16x32_bf16 v[16:19], v[160:163], v[212:215], v[16:19]
	v_mfma_f32_16x16x32_bf16 v[8:11], v[152:155], v[220:223], v[8:11]
	v_mfma_f32_16x16x32_bf16 v[0:3], v[160:163], v[220:223], v[0:3]
	v_mfma_f32_16x16x32_bf16 v[62:65], v[156:159], v[188:191], v[62:65]
	v_mfma_f32_16x16x32_bf16 v[54:57], v[164:167], v[188:191], v[54:57]
	v_mfma_f32_16x16x32_bf16 v[46:49], v[156:159], v[208:211], v[46:49]
	v_mfma_f32_16x16x32_bf16 v[38:41], v[164:167], v[208:211], v[38:41]
	v_mfma_f32_16x16x32_bf16 v[24:27], v[156:159], v[216:219], v[24:27]
	v_mfma_f32_16x16x32_bf16 v[16:19], v[164:167], v[216:219], v[16:19]
	v_mfma_f32_16x16x32_bf16 v[8:11], v[156:159], v[224:227], v[8:11]
	v_mfma_f32_16x16x32_bf16 v[0:3], v[164:167], v[224:227], v[0:3]
	s_setprio 0
	s_setprio 1
	v_mfma_f32_16x16x32_bf16 v[58:61], v[168:171], v[184:187], v[58:61]
	v_mfma_f32_16x16x32_bf16 v[50:53], v[176:179], v[184:187], v[50:53]
	v_mfma_f32_16x16x32_bf16 v[42:45], v[168:171], v[204:207], v[42:45]
	v_mfma_f32_16x16x32_bf16 v[28:31], v[176:179], v[204:207], v[28:31]
	v_mfma_f32_16x16x32_bf16 v[34:37], v[168:171], v[212:215], v[34:37]
	v_mfma_f32_16x16x32_bf16 v[20:23], v[176:179], v[212:215], v[20:23]
	v_mfma_f32_16x16x32_bf16 v[12:15], v[168:171], v[220:223], v[12:15]
	v_mfma_f32_16x16x32_bf16 v[4:7], v[176:179], v[220:223], v[4:7]
	v_mfma_f32_16x16x32_bf16 v[58:61], v[172:175], v[188:191], v[58:61]
	v_mfma_f32_16x16x32_bf16 v[50:53], v[180:183], v[188:191], v[50:53]
	v_mfma_f32_16x16x32_bf16 v[42:45], v[172:175], v[208:211], v[42:45]
	v_mfma_f32_16x16x32_bf16 v[28:31], v[180:183], v[208:211], v[28:31]
	v_mfma_f32_16x16x32_bf16 v[34:37], v[172:175], v[216:219], v[34:37]
	v_mfma_f32_16x16x32_bf16 v[20:23], v[180:183], v[216:219], v[20:23]
	v_mfma_f32_16x16x32_bf16 v[12:15], v[172:175], v[224:227], v[12:15]
	v_mfma_f32_16x16x32_bf16 v[4:7], v[180:183], v[224:227], v[4:7]
	s_setprio 0
	s_barrier
	v_add_u32_e32 v164, 0x18000, v138
	v_add_u32_e32 v180, 0x1c000, v138
	ds_read_b128 v[152:155], v164
	ds_read_b128 v[156:159], v164 offset:1024
	ds_read_b128 v[160:163], v164 offset:2048
	ds_read_b128 v[164:167], v164 offset:3072
	ds_read_b128 v[168:171], v180
	ds_read_b128 v[172:175], v180 offset:1024
	ds_read_b128 v[176:179], v180 offset:2048
	ds_read_b128 v[180:183], v180 offset:3072
	s_add_u32 s6, s34, 0x40000
	s_addc_u32 s7, s35, 0
	v_readfirstlane_b32 s10, v144
	v_lshl_add_u64 v[232:233], s[6:7], 0, v[32:33]
	s_mov_b32 m0, s10
	ds_read_b128 v[184:187], v137 offset:32768
	ds_read_b128 v[188:191], v137 offset:33792
	ds_read_b128 v[204:207], v137 offset:34816
	ds_read_b128 v[208:211], v137 offset:35840
	ds_read_b128 v[212:215], v137 offset:36864
	ds_read_b128 v[216:219], v137 offset:37888
	ds_read_b128 v[220:223], v137 offset:38912
	ds_read_b128 v[224:227], v137 offset:39936
	global_load_lds_dwordx4 v[232:233], off
	v_lshl_add_u64 v[232:233], s[6:7], 0, v[130:131]
	v_readfirstlane_b32 s6, v145
	s_mov_b32 m0, s6
	s_nop 0
	global_load_lds_dwordx4 v[232:233], off
	s_waitcnt vmcnt(8)
	s_waitcnt lgkmcnt(0)
	s_barrier
	s_setprio 1
	s_waitcnt lgkmcnt(0)
	s_nop 0
	v_mfma_f32_16x16x32_bf16 v[126:129], v[152:155], v[184:187], v[126:129]
	v_mfma_f32_16x16x32_bf16 v[118:121], v[160:163], v[184:187], v[118:121]
	v_mfma_f32_16x16x32_bf16 v[110:113], v[152:155], v[204:207], v[110:113]
	v_mfma_f32_16x16x32_bf16 v[102:105], v[160:163], v[204:207], v[102:105]
	v_mfma_f32_16x16x32_bf16 v[94:97], v[152:155], v[212:215], v[94:97]
	v_mfma_f32_16x16x32_bf16 v[86:89], v[160:163], v[212:215], v[86:89]
	v_mfma_f32_16x16x32_bf16 v[78:81], v[152:155], v[220:223], v[78:81]
	v_mfma_f32_16x16x32_bf16 v[70:73], v[160:163], v[220:223], v[70:73]
	v_mfma_f32_16x16x32_bf16 v[126:129], v[156:159], v[188:191], v[126:129]
	v_mfma_f32_16x16x32_bf16 v[118:121], v[164:167], v[188:191], v[118:121]
	v_mfma_f32_16x16x32_bf16 v[110:113], v[156:159], v[208:211], v[110:113]
	v_mfma_f32_16x16x32_bf16 v[102:105], v[164:167], v[208:211], v[102:105]
	v_mfma_f32_16x16x32_bf16 v[94:97], v[156:159], v[216:219], v[94:97]
	v_mfma_f32_16x16x32_bf16 v[86:89], v[164:167], v[216:219], v[86:89]
	v_mfma_f32_16x16x32_bf16 v[78:81], v[156:159], v[224:227], v[78:81]
	v_mfma_f32_16x16x32_bf16 v[70:73], v[164:167], v[224:227], v[70:73]
	s_setprio 0
	s_setprio 1
	v_mfma_f32_16x16x32_bf16 v[122:125], v[168:171], v[184:187], v[122:125]
	v_mfma_f32_16x16x32_bf16 v[114:117], v[176:179], v[184:187], v[114:117]
	v_mfma_f32_16x16x32_bf16 v[106:109], v[168:171], v[204:207], v[106:109]
	v_mfma_f32_16x16x32_bf16 v[98:101], v[176:179], v[204:207], v[98:101]
	v_mfma_f32_16x16x32_bf16 v[90:93], v[168:171], v[212:215], v[90:93]
	v_mfma_f32_16x16x32_bf16 v[82:85], v[176:179], v[212:215], v[82:85]
	v_mfma_f32_16x16x32_bf16 v[74:77], v[168:171], v[220:223], v[74:77]
	v_mfma_f32_16x16x32_bf16 v[66:69], v[176:179], v[220:223], v[66:69]
	v_mfma_f32_16x16x32_bf16 v[122:125], v[172:175], v[188:191], v[122:125]
	v_mfma_f32_16x16x32_bf16 v[114:117], v[180:183], v[188:191], v[114:117]
	v_mfma_f32_16x16x32_bf16 v[106:109], v[172:175], v[208:211], v[106:109]
	v_mfma_f32_16x16x32_bf16 v[98:101], v[180:183], v[208:211], v[98:101]
	v_mfma_f32_16x16x32_bf16 v[90:93], v[172:175], v[216:219], v[90:93]
	v_mfma_f32_16x16x32_bf16 v[82:85], v[180:183], v[216:219], v[82:85]
	v_mfma_f32_16x16x32_bf16 v[74:77], v[172:175], v[224:227], v[74:77]
	v_mfma_f32_16x16x32_bf16 v[66:69], v[180:183], v[224:227], v[66:69]
	s_setprio 0
	s_barrier
; #define STAGE(bufoff, GB) do { const char* g_ = (GB); \
;         _Pragma("unroll") for (int i_ = 0; i_ < 2; ++i_) __builtin_amdgcn_global_load_lds((const unsigned*)(g_ + voff[i_]), (LAS3 unsigned*)(L + (bufoff) + stoff + i_ * 8192), 16, 0, 0); } while (0)
; #define LDA(dst, b, h) do { _Pragma("unroll") for (int m = 0; m < 4; ++m) _Pragma("unroll") for (int k = 0; k < 2; ++k) dst[m][k] = *(const LAS3 bf16x8*)(L + SA(b, h) + aoff + m * 2048 + k * 1024); } while (0)
; #define WAIT_V(n) asm volatile("s_waitcnt vmcnt(" #n ")" ::: "memory")
; #define WAIT_L(n) asm volatile("s_waitcnt lgkmcnt(" #n ")" ::: "memory")
; #define BAR __builtin_amdgcn_s_barrier()
; #define SCHED __builtin_amdgcn_sched_barrier(0)
; template <int EPI>
; DI void gemm_phase(const bf16_t* __restrict__ A, const bf16_t* __restrict__ Bt, const int K, const int N, const Params& p, const int layer_j, char* lds) {
;     ...
;             LDA(At, 1, 1); STAGE(SB(1, 0), b3); STAGE(SB(1, 1), b3 + hstep); STAGE(SA(1, 0), a3);
;             WAIT_V(8); WAIT_L(0); BAR; MMA(1, 0, At, B0); MMA(1, 1, At, B1); BAR; SCHED;
;         }
	v_readfirstlane_b32 s6, v146
	v_lshl_add_u64 v[192:193], v[192:193], 0, s[94:95]
	s_mov_b32 m0, s6
	v_readfirstlane_b32 s6, v147
	ds_read_b128 v[184:187], v137 offset:49152
	ds_read_b128 v[188:191], v137 offset:50176
	ds_read_b128 v[204:207], v137 offset:51200
	ds_read_b128 v[208:211], v137 offset:52224
	ds_read_b128 v[212:215], v137 offset:53248
	ds_read_b128 v[216:219], v137 offset:54272
	ds_read_b128 v[220:223], v137 offset:55296
	ds_read_b128 v[224:227], v137 offset:56320
	global_load_lds_dwordx4 v[192:193], off
	s_mov_b32 m0, s6
	s_add_u32 s6, s30, 0x40080
	v_lshl_add_u64 v[192:193], v[194:195], 0, s[94:95]
	s_addc_u32 s7, s31, 0
	v_readfirstlane_b32 s10, v150
	global_load_lds_dwordx4 v[192:193], off
	v_lshl_add_u64 v[192:193], s[6:7], 0, v[32:33]
	s_mov_b32 m0, s10
	s_nop 0
	global_load_lds_dwordx4 v[192:193], off
	v_lshl_add_u64 v[192:193], s[6:7], 0, v[130:131]
	v_readfirstlane_b32 s6, v151
	s_mov_b32 m0, s6
	v_readfirstlane_b32 s6, v148
	global_load_lds_dwordx4 v[192:193], off
	v_lshl_add_u64 v[192:193], v[228:229], 0, s[94:95]
	s_mov_b32 m0, s6
	v_readfirstlane_b32 s6, v149
	global_load_lds_dwordx4 v[192:193], off
	v_lshl_add_u64 v[192:193], v[230:231], 0, s[94:95]
	s_mov_b32 m0, s6
	s_nop 0
	global_load_lds_dwordx4 v[192:193], off
	s_waitcnt vmcnt(8)
	s_waitcnt lgkmcnt(0)
	s_barrier
	s_setprio 1
	s_waitcnt lgkmcnt(0)
	v_mfma_f32_16x16x32_bf16 v[62:65], v[152:155], v[184:187], v[62:65]
	v_mfma_f32_16x16x32_bf16 v[54:57], v[160:163], v[184:187], v[54:57]
	v_mfma_f32_16x16x32_bf16 v[46:49], v[152:155], v[204:207], v[46:49]
	v_mfma_f32_16x16x32_bf16 v[38:41], v[160:163], v[204:207], v[38:41]
	v_mfma_f32_16x16x32_bf16 v[24:27], v[152:155], v[212:215], v[24:27]
	v_mfma_f32_16x16x32_bf16 v[16:19], v[160:163], v[212:215], v[16:19]
	v_mfma_f32_16x16x32_bf16 v[8:11], v[152:155], v[220:223], v[8:11]
	v_mfma_f32_16x16x32_bf16 v[0:3], v[160:163], v[220:223], v[0:3]
	v_mfma_f32_16x16x32_bf16 v[62:65], v[156:159], v[188:191], v[62:65]
	v_mfma_f32_16x16x32_bf16 v[54:57], v[164:167], v[188:191], v[54:57]
	v_mfma_f32_16x16x32_bf16 v[46:49], v[156:159], v[208:211], v[46:49]
	v_mfma_f32_16x16x32_bf16 v[38:41], v[164:167], v[208:211], v[38:41]
	v_mfma_f32_16x16x32_bf16 v[24:27], v[156:159], v[216:219], v[24:27]
	v_mfma_f32_16x16x32_bf16 v[16:19], v[164:167], v[216:219], v[16:19]
	v_mfma_f32_16x16x32_bf16 v[8:11], v[156:159], v[224:227], v[8:11]
	v_mfma_f32_16x16x32_bf16 v[0:3], v[164:167], v[224:227], v[0:3]
	s_setprio 0
	s_setprio 1
	v_mfma_f32_16x16x32_bf16 v[58:61], v[168:171], v[184:187], v[58:61]
	v_mfma_f32_16x16x32_bf16 v[50:53], v[176:179], v[184:187], v[50:53]
	v_mfma_f32_16x16x32_bf16 v[42:45], v[168:171], v[204:207], v[42:45]
	v_mfma_f32_16x16x32_bf16 v[28:31], v[176:179], v[204:207], v[28:31]
	v_mfma_f32_16x16x32_bf16 v[34:37], v[168:171], v[212:215], v[34:37]
	v_mfma_f32_16x16x32_bf16 v[20:23], v[176:179], v[212:215], v[20:23]
	v_mfma_f32_16x16x32_bf16 v[12:15], v[168:171], v[220:223], v[12:15]
	v_mfma_f32_16x16x32_bf16 v[4:7], v[176:179], v[220:223], v[4:7]
	v_mfma_f32_16x16x32_bf16 v[58:61], v[172:175], v[188:191], v[58:61]
	v_mfma_f32_16x16x32_bf16 v[50:53], v[180:183], v[188:191], v[50:53]
	v_mfma_f32_16x16x32_bf16 v[42:45], v[172:175], v[208:211], v[42:45]
	v_mfma_f32_16x16x32_bf16 v[28:31], v[180:183], v[208:211], v[28:31]
	v_mfma_f32_16x16x32_bf16 v[34:37], v[172:175], v[216:219], v[34:37]
	v_mfma_f32_16x16x32_bf16 v[20:23], v[180:183], v[216:219], v[20:23]
	v_mfma_f32_16x16x32_bf16 v[12:15], v[172:175], v[224:227], v[12:15]
	v_mfma_f32_16x16x32_bf16 v[4:7], v[180:183], v[224:227], v[4:7]
	s_setprio 0
	s_barrier
	s_add_i32 s37, s37, 2
	s_add_u32 s28, s28, 0x100
	s_addc_u32 s29, s29, 0
	s_cmp_gt_u32 s37, 13
	s_cbranch_scc0 .LBB0_43
	v_readlane_b32 s6, v254, 12
	v_readlane_b32 s7, v254, 13
	s_and_b64 vcc, exec, s[6:7]
	s_cbranch_vccz .LBB0_46
	s_barrier

; #define STAGE(bufoff, GB) do { const char* g_ = (GB); \
;         _Pragma("unroll") for (int i_ = 0; i_ < 2; ++i_) __builtin_amdgcn_global_load_lds((const unsigned*)(g_ + voff[i_]), (LAS3 unsigned*)(L + (bufoff) + stoff + i_ * 8192), 16, 0, 0); } while (0)
; #define LDA(dst, b, h) do { _Pragma("unroll") for (int m = 0; m < 4; ++m) _Pragma("unroll") for (int k = 0; k < 2; ++k) dst[m][k] = *(const LAS3 bf16x8*)(L + SA(b, h) + aoff + m * 2048 + k * 1024); } while (0)
; #define LDB(dst, b, h) do { _Pragma("unroll") for (int n = 0; n < 2; ++n) _Pragma("unroll") for (int k = 0; k < 2; ++k) dst[n][k] = *(const LAS3 bf16x8*)(L + SB(b, h) + boff + n * 2048 + k * 1024); } while (0)
; #define WAIT_V(n) asm volatile("s_waitcnt vmcnt(" #n ")" ::: "memory")
; #define WAIT_L(n) asm volatile("s_waitcnt lgkmcnt(" #n ")" ::: "memory")
; #define BAR __builtin_amdgcn_s_barrier()
; #define SCHED __builtin_amdgcn_sched_barrier(0)
; template <int EPI>
; DI void gemm_phase(const bf16_t* __restrict__ A, const bf16_t* __restrict__ Bt, const int K, const int N, const Params& p, const int layer_j, char* lds) {
;     ...
;             const bool last = (t == nt - 2);
;             const char* a1 = cA + (size_t)(t + 1) * kstep;
;             const char* a2 = last ? nA : cA + (size_t)(t + 2) * kstep; const char* b2 = last ? nB : cB + (size_t)(t + 2) * kstep;
;             const char* a3 = a2 + kstep; const char* b3 = b2 + kstep;
;             LDB(B0, 0, 0); LDB(B1, 0, 1); SCHED; LDA(At, 0, 0); STAGE(SA(1, 1), a1 + hstep);
;             WAIT_V(8); WAIT_L(0); BAR; MMA(0, 0, At, B0); MMA(0, 1, At, B1); BAR; SCHED;
;             LDA(At, 0, 1); STAGE(SB(0, 0), b2); STAGE(SB(0, 1), b2 + hstep); STAGE(SA(0, 0), a2);
;             WAIT_V(8); WAIT_L(0); BAR; MMA(1, 0, At, B0); MMA(1, 1, At, B1); BAR; SCHED;
.LBB0_106:
	v_add_u32_e32 v164, 0x10000, v138
	v_add_u32_e32 v180, 0x14000, v138
	ds_read_b128 v[152:155], v164
	ds_read_b128 v[156:159], v164 offset:1024
	ds_read_b128 v[160:163], v164 offset:2048
	ds_read_b128 v[164:167], v164 offset:3072
	ds_read_b128 v[168:171], v180
	ds_read_b128 v[172:175], v180 offset:1024
	ds_read_b128 v[176:179], v180 offset:2048
	ds_read_b128 v[180:183], v180 offset:3072
	s_add_i32 s39, s18, 2
	s_add_u32 s64, s16, 0x80
	s_addc_u32 s19, s17, 0
	s_cmp_eq_u32 s25, s18
	s_cselect_b32 s18, s14, s64
	s_cselect_b32 s19, s15, s19
	s_cselect_b32 s65, s36, s38
	s_cselect_b32 s64, s35, s37
	v_add_u32_e32 v194, 0xc000, v136
	v_lshl_add_u64 v[192:193], s[16:17], 0, v[134:135]
	v_readfirstlane_b32 s66, v194
	v_add_u32_e32 v194, 0xe000, v136
	s_mov_b32 m0, s66
	v_readfirstlane_b32 s66, v194
	ds_read_b128 v[184:187], v137
	ds_read_b128 v[188:191], v137 offset:1024
	ds_read_b128 v[204:207], v137 offset:2048
	ds_read_b128 v[208:211], v137 offset:3072
	ds_read_b128 v[212:215], v137 offset:4096
	ds_read_b128 v[216:219], v137 offset:5120
	ds_read_b128 v[220:223], v137 offset:6144
	ds_read_b128 v[224:227], v137 offset:7168
	global_load_lds_dwordx4 v[192:193], off
	v_lshl_add_u64 v[192:193], s[16:17], 0, v[132:133]
	s_mov_b32 m0, s66
	s_nop 0
	global_load_lds_dwordx4 v[192:193], off
	s_waitcnt vmcnt(8)
	s_waitcnt lgkmcnt(0)
	s_barrier
	s_setprio 1
	s_waitcnt lgkmcnt(0)
	s_nop 0
	v_mfma_f32_16x16x32_bf16 v[126:129], v[152:155], v[184:187], v[126:129]
	v_mfma_f32_16x16x32_bf16 v[122:125], v[160:163], v[184:187], v[122:125]
	v_mfma_f32_16x16x32_bf16 v[110:113], v[152:155], v[204:207], v[110:113]
	v_mfma_f32_16x16x32_bf16 v[106:109], v[160:163], v[204:207], v[106:109]
	v_mfma_f32_16x16x32_bf16 v[94:97], v[152:155], v[212:215], v[94:97]
	v_mfma_f32_16x16x32_bf16 v[90:93], v[160:163], v[212:215], v[90:93]
	v_mfma_f32_16x16x32_bf16 v[78:81], v[152:155], v[220:223], v[78:81]
	v_mfma_f32_16x16x32_bf16 v[74:77], v[160:163], v[220:223], v[74:77]
	v_mfma_f32_16x16x32_bf16 v[126:129], v[156:159], v[188:191], v[126:129]
	v_mfma_f32_16x16x32_bf16 v[122:125], v[164:167], v[188:191], v[122:125]
	v_mfma_f32_16x16x32_bf16 v[110:113], v[156:159], v[208:211], v[110:113]
	v_mfma_f32_16x16x32_bf16 v[106:109], v[164:167], v[208:211], v[106:109]
	v_mfma_f32_16x16x32_bf16 v[94:97], v[156:159], v[216:219], v[94:97]
	v_mfma_f32_16x16x32_bf16 v[90:93], v[164:167], v[216:219], v[90:93]
	v_mfma_f32_16x16x32_bf16 v[78:81], v[156:159], v[224:227], v[78:81]
	v_mfma_f32_16x16x32_bf16 v[74:77], v[164:167], v[224:227], v[74:77]
	s_setprio 0
	s_setprio 1
	v_mfma_f32_16x16x32_bf16 v[118:121], v[168:171], v[184:187], v[118:121]
	v_mfma_f32_16x16x32_bf16 v[114:117], v[176:179], v[184:187], v[114:117]
	v_mfma_f32_16x16x32_bf16 v[102:105], v[168:171], v[204:207], v[102:105]
	v_mfma_f32_16x16x32_bf16 v[98:101], v[176:179], v[204:207], v[98:101]
	v_mfma_f32_16x16x32_bf16 v[86:89], v[168:171], v[212:215], v[86:89]
	v_mfma_f32_16x16x32_bf16 v[82:85], v[176:179], v[212:215], v[82:85]
	v_mfma_f32_16x16x32_bf16 v[70:73], v[168:171], v[220:223], v[70:73]
	v_mfma_f32_16x16x32_bf16 v[66:69], v[176:179], v[220:223], v[66:69]
	v_mfma_f32_16x16x32_bf16 v[118:121], v[172:175], v[188:191], v[118:121]
	v_mfma_f32_16x16x32_bf16 v[114:117], v[180:183], v[188:191], v[114:117]
	v_mfma_f32_16x16x32_bf16 v[102:105], v[172:175], v[208:211], v[102:105]
	v_mfma_f32_16x16x32_bf16 v[98:101], v[180:183], v[208:211], v[98:101]
	v_mfma_f32_16x16x32_bf16 v[86:89], v[172:175], v[216:219], v[86:89]
	v_mfma_f32_16x16x32_bf16 v[82:85], v[180:183], v[216:219], v[82:85]
	v_mfma_f32_16x16x32_bf16 v[70:73], v[172:175], v[224:227], v[70:73]
	v_mfma_f32_16x16x32_bf16 v[66:69], v[180:183], v[224:227], v[66:69]
	s_setprio 0
	s_barrier
	v_readfirstlane_b32 s66, v139
	v_lshl_add_u64 v[192:193], s[64:65], 0, v[32:33]
	s_mov_b32 m0, s66
	v_lshl_add_u64 v[194:195], s[64:65], 0, v[130:131]
	v_readfirstlane_b32 s66, v140
	s_add_u32 s64, s64, s88
	ds_read_b128 v[184:187], v137 offset:16384
	ds_read_b128 v[188:191], v137 offset:17408
	ds_read_b128 v[204:207], v137 offset:18432
	ds_read_b128 v[208:211], v137 offset:19456
	ds_read_b128 v[212:215], v137 offset:20480
	ds_read_b128 v[216:219], v137 offset:21504
	ds_read_b128 v[220:223], v137 offset:22528
	ds_read_b128 v[224:227], v137 offset:23552
	global_load_lds_dwordx4 v[192:193], off
	s_mov_b32 m0, s66
	s_addc_u32 s65, s65, 0
	v_readfirstlane_b32 s66, v141
	global_load_lds_dwordx4 v[194:195], off
	v_lshl_add_u64 v[228:229], s[64:65], 0, v[32:33]
	s_mov_b32 m0, s66
	v_lshl_add_u64 v[230:231], s[64:65], 0, v[130:131]
	v_readfirstlane_b32 s64, v142
	global_load_lds_dwordx4 v[228:229], off
	s_mov_b32 m0, s64
	v_readfirstlane_b32 s64, v136
	global_load_lds_dwordx4 v[230:231], off
	v_lshl_add_u64 v[232:233], s[18:19], 0, v[32:33]
	s_mov_b32 m0, s64
	v_readfirstlane_b32 s64, v143
	global_load_lds_dwordx4 v[232:233], off
	v_lshl_add_u64 v[234:235], s[18:19], 0, v[130:131]
	s_mov_b32 m0, s64
	s_nop 0
	global_load_lds_dwordx4 v[234:235], off
	s_waitcnt vmcnt(8)
	s_waitcnt lgkmcnt(0)
	s_barrier
; #define STAGE(bufoff, GB) do { const char* g_ = (GB); \
;         _Pragma("unroll") for (int i_ = 0; i_ < 2; ++i_) __builtin_amdgcn_global_load_lds((const unsigned*)(g_ + voff[i_]), (LAS3 unsigned*)(L + (bufoff) + stoff + i_ * 8192), 16, 0, 0); } while (0)
; #define LDA(dst, b, h) do { _Pragma("unroll") for (int m = 0; m < 4; ++m) _Pragma("unroll") for (int k = 0; k < 2; ++k) dst[m][k] = *(const LAS3 bf16x8*)(L + SA(b, h) + aoff + m * 2048 + k * 1024); } while (0)
; #define LDB(dst, b, h) do { _Pragma("unroll") for (int n = 0; n < 2; ++n) _Pragma("unroll") for (int k = 0; k < 2; ++k) dst[n][k] = *(const LAS3 bf16x8*)(L + SB(b, h) + boff + n * 2048 + k * 1024); } while (0)
; #define WAIT_V(n) asm volatile("s_waitcnt vmcnt(" #n ")" ::: "memory")
; #define WAIT_L(n) asm volatile("s_waitcnt lgkmcnt(" #n ")" ::: "memory")
; #define BAR __builtin_amdgcn_s_barrier()
; #define SCHED __builtin_amdgcn_sched_barrier(0)
; template <int EPI>
; DI void gemm_phase(const bf16_t* __restrict__ A, const bf16_t* __restrict__ Bt, const int K, const int N, const Params& p, const int layer_j, char* lds) {
;     ...
;             WAIT_V(8); WAIT_L(0); BAR; MMA(1, 0, At, B0); MMA(1, 1, At, B1); BAR; SCHED;
;             LDB(B0, 1, 0); LDB(B1, 1, 1); SCHED; LDA(At, 1, 0); STAGE(SA(0, 1), a2 + hstep);
;             WAIT_V(8); WAIT_L(0); BAR; MMA(0, 0, At, B0); MMA(0, 1, At, B1); BAR; SCHED;
	s_setprio 1
	s_waitcnt lgkmcnt(0)
	v_mfma_f32_16x16x32_bf16 v[62:65], v[152:155], v[184:187], v[62:65]
	v_mfma_f32_16x16x32_bf16 v[58:61], v[160:163], v[184:187], v[58:61]
	v_mfma_f32_16x16x32_bf16 v[38:41], v[152:155], v[204:207], v[38:41]
	v_mfma_f32_16x16x32_bf16 v[24:27], v[160:163], v[204:207], v[24:27]
	v_mfma_f32_16x16x32_bf16 v[12:15], v[152:155], v[212:215], v[12:15]
	v_mfma_f32_16x16x32_bf16 v[8:11], v[160:163], v[212:215], v[8:11]
	v_mfma_f32_16x16x32_bf16 v[4:7], v[152:155], v[220:223], v[4:7]
	v_mfma_f32_16x16x32_bf16 v[0:3], v[160:163], v[220:223], v[0:3]
	v_mfma_f32_16x16x32_bf16 v[62:65], v[156:159], v[188:191], v[62:65]
	v_mfma_f32_16x16x32_bf16 v[58:61], v[164:167], v[188:191], v[58:61]
	v_mfma_f32_16x16x32_bf16 v[38:41], v[156:159], v[208:211], v[38:41]
	v_mfma_f32_16x16x32_bf16 v[24:27], v[164:167], v[208:211], v[24:27]
	v_mfma_f32_16x16x32_bf16 v[12:15], v[156:159], v[216:219], v[12:15]
	v_mfma_f32_16x16x32_bf16 v[8:11], v[164:167], v[216:219], v[8:11]
	v_mfma_f32_16x16x32_bf16 v[4:7], v[156:159], v[224:227], v[4:7]
	v_mfma_f32_16x16x32_bf16 v[0:3], v[164:167], v[224:227], v[0:3]
	s_setprio 0
	s_setprio 1
	v_mfma_f32_16x16x32_bf16 v[46:49], v[168:171], v[184:187], v[46:49]
	v_mfma_f32_16x16x32_bf16 v[42:45], v[176:179], v[184:187], v[42:45]
	v_mfma_f32_16x16x32_bf16 v[20:23], v[168:171], v[204:207], v[20:23]
	v_mfma_f32_16x16x32_bf16 v[16:19], v[176:179], v[204:207], v[16:19]
	v_mfma_f32_16x16x32_bf16 v[50:53], v[168:171], v[212:215], v[50:53]
	v_mfma_f32_16x16x32_bf16 v[54:57], v[176:179], v[212:215], v[54:57]
	v_mfma_f32_16x16x32_bf16 v[28:31], v[168:171], v[220:223], v[28:31]
	v_mfma_f32_16x16x32_bf16 v[34:37], v[176:179], v[220:223], v[34:37]
	v_mfma_f32_16x16x32_bf16 v[46:49], v[172:175], v[188:191], v[46:49]
	v_mfma_f32_16x16x32_bf16 v[42:45], v[180:183], v[188:191], v[42:45]
	v_mfma_f32_16x16x32_bf16 v[20:23], v[172:175], v[208:211], v[20:23]
	v_mfma_f32_16x16x32_bf16 v[16:19], v[180:183], v[208:211], v[16:19]
	v_mfma_f32_16x16x32_bf16 v[50:53], v[172:175], v[216:219], v[50:53]
	v_mfma_f32_16x16x32_bf16 v[54:57], v[180:183], v[216:219], v[54:57]
	v_mfma_f32_16x16x32_bf16 v[28:31], v[172:175], v[224:227], v[28:31]
	v_mfma_f32_16x16x32_bf16 v[34:37], v[180:183], v[224:227], v[34:37]
	s_setprio 0
	s_barrier
	v_add_u32_e32 v164, 0x18000, v138
	v_add_u32_e32 v180, 0x1c000, v138
	ds_read_b128 v[152:155], v164
	ds_read_b128 v[156:159], v164 offset:1024
	ds_read_b128 v[160:163], v164 offset:2048
	ds_read_b128 v[164:167], v164 offset:3072
	ds_read_b128 v[168:171], v180
	ds_read_b128 v[172:175], v180 offset:1024
	ds_read_b128 v[176:179], v180 offset:2048
	ds_read_b128 v[180:183], v180 offset:3072
	s_add_u32 s18, s18, s88
	s_addc_u32 s19, s19, 0
	v_readfirstlane_b32 s64, v144
	v_lshl_add_u64 v[236:237], s[18:19], 0, v[32:33]
	s_mov_b32 m0, s64
	ds_read_b128 v[184:187], v137 offset:32768
	ds_read_b128 v[188:191], v137 offset:33792
	ds_read_b128 v[204:207], v137 offset:34816
	ds_read_b128 v[208:211], v137 offset:35840
	ds_read_b128 v[212:215], v137 offset:36864
	ds_read_b128 v[216:219], v137 offset:37888
	ds_read_b128 v[220:223], v137 offset:38912
	ds_read_b128 v[224:227], v137 offset:39936
	global_load_lds_dwordx4 v[236:237], off
	v_lshl_add_u64 v[236:237], s[18:19], 0, v[130:131]
	v_readfirstlane_b32 s18, v145
	s_mov_b32 m0, s18
	s_nop 0
	global_load_lds_dwordx4 v[236:237], off
	s_waitcnt vmcnt(8)
	s_waitcnt lgkmcnt(0)
	s_barrier
	s_setprio 1
	s_waitcnt lgkmcnt(0)
	v_mfma_f32_16x16x32_bf16 v[126:129], v[152:155], v[184:187], v[126:129]
	v_mfma_f32_16x16x32_bf16 v[122:125], v[160:163], v[184:187], v[122:125]
	v_mfma_f32_16x16x32_bf16 v[110:113], v[152:155], v[204:207], v[110:113]
	v_mfma_f32_16x16x32_bf16 v[106:109], v[160:163], v[204:207], v[106:109]
	v_mfma_f32_16x16x32_bf16 v[94:97], v[152:155], v[212:215], v[94:97]
	v_mfma_f32_16x16x32_bf16 v[90:93], v[160:163], v[212:215], v[90:93]
	v_mfma_f32_16x16x32_bf16 v[78:81], v[152:155], v[220:223], v[78:81]
	v_mfma_f32_16x16x32_bf16 v[74:77], v[160:163], v[220:223], v[74:77]
	v_mfma_f32_16x16x32_bf16 v[126:129], v[156:159], v[188:191], v[126:129]
	v_mfma_f32_16x16x32_bf16 v[122:125], v[164:167], v[188:191], v[122:125]
	v_mfma_f32_16x16x32_bf16 v[110:113], v[156:159], v[208:211], v[110:113]
	v_mfma_f32_16x16x32_bf16 v[106:109], v[164:167], v[208:211], v[106:109]
	v_mfma_f32_16x16x32_bf16 v[94:97], v[156:159], v[216:219], v[94:97]
	v_mfma_f32_16x16x32_bf16 v[90:93], v[164:167], v[216:219], v[90:93]
	v_mfma_f32_16x16x32_bf16 v[78:81], v[156:159], v[224:227], v[78:81]
	v_mfma_f32_16x16x32_bf16 v[74:77], v[164:167], v[224:227], v[74:77]
	s_setprio 0
	s_setprio 1
	v_mfma_f32_16x16x32_bf16 v[118:121], v[168:171], v[184:187], v[118:121]
	v_mfma_f32_16x16x32_bf16 v[114:117], v[176:179], v[184:187], v[114:117]
	v_mfma_f32_16x16x32_bf16 v[102:105], v[168:171], v[204:207], v[102:105]
	v_mfma_f32_16x16x32_bf16 v[98:101], v[176:179], v[204:207], v[98:101]
	v_mfma_f32_16x16x32_bf16 v[86:89], v[168:171], v[212:215], v[86:89]
	v_mfma_f32_16x16x32_bf16 v[82:85], v[176:179], v[212:215], v[82:85]
	v_mfma_f32_16x16x32_bf16 v[70:73], v[168:171], v[220:223], v[70:73]
	v_mfma_f32_16x16x32_bf16 v[66:69], v[176:179], v[220:223], v[66:69]
	v_mfma_f32_16x16x32_bf16 v[118:121], v[172:175], v[188:191], v[118:121]
	v_mfma_f32_16x16x32_bf16 v[114:117], v[180:183], v[188:191], v[114:117]
	v_mfma_f32_16x16x32_bf16 v[102:105], v[172:175], v[208:211], v[102:105]
	v_mfma_f32_16x16x32_bf16 v[98:101], v[180:183], v[208:211], v[98:101]
	v_mfma_f32_16x16x32_bf16 v[86:89], v[172:175], v[216:219], v[86:89]
	v_mfma_f32_16x16x32_bf16 v[82:85], v[180:183], v[216:219], v[82:85]
	v_mfma_f32_16x16x32_bf16 v[70:73], v[172:175], v[224:227], v[70:73]
	v_mfma_f32_16x16x32_bf16 v[66:69], v[180:183], v[224:227], v[66:69]
	s_setprio 0
	s_barrier
; #define STAGE(bufoff, GB) do { const char* g_ = (GB); \
;         _Pragma("unroll") for (int i_ = 0; i_ < 2; ++i_) __builtin_amdgcn_global_load_lds((const unsigned*)(g_ + voff[i_]), (LAS3 unsigned*)(L + (bufoff) + stoff + i_ * 8192), 16, 0, 0); } while (0)
; #define LDA(dst, b, h) do { _Pragma("unroll") for (int m = 0; m < 4; ++m) _Pragma("unroll") for (int k = 0; k < 2; ++k) dst[m][k] = *(const LAS3 bf16x8*)(L + SA(b, h) + aoff + m * 2048 + k * 1024); } while (0)
; #define WAIT_V(n) asm volatile("s_waitcnt vmcnt(" #n ")" ::: "memory")
; #define WAIT_L(n) asm volatile("s_waitcnt lgkmcnt(" #n ")" ::: "memory")
; #define BAR __builtin_amdgcn_s_barrier()
; #define SCHED __builtin_amdgcn_sched_barrier(0)
; template <int EPI>
; DI void gemm_phase(const bf16_t* __restrict__ A, const bf16_t* __restrict__ Bt, const int K, const int N, const Params& p, const int layer_j, char* lds) {
;     ...
;             LDA(At, 1, 1); STAGE(SB(1, 0), b3); STAGE(SB(1, 1), b3 + hstep); STAGE(SA(1, 0), a3);
;             WAIT_V(8); WAIT_L(0); BAR; MMA(1, 0, At, B0); MMA(1, 1, At, B1); BAR; SCHED;
;         }
;         if (wr == 0) BAR;
	v_readfirstlane_b32 s18, v146
	v_lshl_add_u64 v[192:193], v[192:193], 0, s[94:95]
	s_mov_b32 m0, s18
	v_readfirstlane_b32 s18, v147
	ds_read_b128 v[184:187], v137 offset:49152
	ds_read_b128 v[188:191], v137 offset:50176
	ds_read_b128 v[204:207], v137 offset:51200
	ds_read_b128 v[208:211], v137 offset:52224
	ds_read_b128 v[212:215], v137 offset:53248
	ds_read_b128 v[216:219], v137 offset:54272
	ds_read_b128 v[220:223], v137 offset:55296
	ds_read_b128 v[224:227], v137 offset:56320
	global_load_lds_dwordx4 v[192:193], off
	v_lshl_add_u64 v[192:193], v[194:195], 0, s[94:95]
	s_mov_b32 m0, s18
	v_readfirstlane_b32 s18, v150
	global_load_lds_dwordx4 v[192:193], off
	v_lshl_add_u64 v[192:193], v[228:229], 0, s[94:95]
	s_mov_b32 m0, s18
	v_readfirstlane_b32 s18, v151
	global_load_lds_dwordx4 v[192:193], off
	v_lshl_add_u64 v[192:193], v[230:231], 0, s[94:95]
	s_mov_b32 m0, s18
	v_readfirstlane_b32 s18, v148
	global_load_lds_dwordx4 v[192:193], off
	v_lshl_add_u64 v[192:193], v[232:233], 0, s[94:95]
	s_mov_b32 m0, s18
	v_readfirstlane_b32 s18, v149
	global_load_lds_dwordx4 v[192:193], off
	v_lshl_add_u64 v[192:193], v[234:235], 0, s[94:95]
	s_mov_b32 m0, s18
	s_nop 0
	global_load_lds_dwordx4 v[192:193], off
	s_waitcnt vmcnt(8)
	s_waitcnt lgkmcnt(0)
	s_barrier
	s_setprio 1
	s_waitcnt lgkmcnt(0)
	v_mfma_f32_16x16x32_bf16 v[62:65], v[152:155], v[184:187], v[62:65]
	v_mfma_f32_16x16x32_bf16 v[58:61], v[160:163], v[184:187], v[58:61]
	v_mfma_f32_16x16x32_bf16 v[38:41], v[152:155], v[204:207], v[38:41]
	v_mfma_f32_16x16x32_bf16 v[24:27], v[160:163], v[204:207], v[24:27]
	v_mfma_f32_16x16x32_bf16 v[12:15], v[152:155], v[212:215], v[12:15]
	v_mfma_f32_16x16x32_bf16 v[8:11], v[160:163], v[212:215], v[8:11]
	v_mfma_f32_16x16x32_bf16 v[4:7], v[152:155], v[220:223], v[4:7]
	v_mfma_f32_16x16x32_bf16 v[0:3], v[160:163], v[220:223], v[0:3]
	v_mfma_f32_16x16x32_bf16 v[62:65], v[156:159], v[188:191], v[62:65]
	v_mfma_f32_16x16x32_bf16 v[58:61], v[164:167], v[188:191], v[58:61]
	v_mfma_f32_16x16x32_bf16 v[38:41], v[156:159], v[208:211], v[38:41]
	v_mfma_f32_16x16x32_bf16 v[24:27], v[164:167], v[208:211], v[24:27]
	v_mfma_f32_16x16x32_bf16 v[12:15], v[156:159], v[216:219], v[12:15]
	v_mfma_f32_16x16x32_bf16 v[8:11], v[164:167], v[216:219], v[8:11]
	v_mfma_f32_16x16x32_bf16 v[4:7], v[156:159], v[224:227], v[4:7]
	v_mfma_f32_16x16x32_bf16 v[0:3], v[164:167], v[224:227], v[0:3]
	s_setprio 0
	s_setprio 1
	v_mfma_f32_16x16x32_bf16 v[46:49], v[168:171], v[184:187], v[46:49]
	v_mfma_f32_16x16x32_bf16 v[42:45], v[176:179], v[184:187], v[42:45]
	v_mfma_f32_16x16x32_bf16 v[20:23], v[168:171], v[204:207], v[20:23]
	v_mfma_f32_16x16x32_bf16 v[16:19], v[176:179], v[204:207], v[16:19]
	v_mfma_f32_16x16x32_bf16 v[50:53], v[168:171], v[212:215], v[50:53]
	v_mfma_f32_16x16x32_bf16 v[54:57], v[176:179], v[212:215], v[54:57]
	v_mfma_f32_16x16x32_bf16 v[28:31], v[168:171], v[220:223], v[28:31]
	v_mfma_f32_16x16x32_bf16 v[34:37], v[176:179], v[220:223], v[34:37]
	v_mfma_f32_16x16x32_bf16 v[46:49], v[172:175], v[188:191], v[46:49]
	v_mfma_f32_16x16x32_bf16 v[42:45], v[180:183], v[188:191], v[42:45]
	v_mfma_f32_16x16x32_bf16 v[20:23], v[172:175], v[208:211], v[20:23]
	v_mfma_f32_16x16x32_bf16 v[16:19], v[180:183], v[208:211], v[16:19]
	v_mfma_f32_16x16x32_bf16 v[50:53], v[172:175], v[216:219], v[50:53]
	v_mfma_f32_16x16x32_bf16 v[54:57], v[180:183], v[216:219], v[54:57]
	v_mfma_f32_16x16x32_bf16 v[28:31], v[172:175], v[224:227], v[28:31]
	v_mfma_f32_16x16x32_bf16 v[34:37], v[180:183], v[224:227], v[34:37]
	s_setprio 0
	s_barrier
	s_add_u32 s37, s37, 0x100
	s_addc_u32 s38, s38, 0
	s_add_u32 s16, s16, 0x100
	s_addc_u32 s17, s17, 0
	s_cmp_ge_u32 s39, s24
	s_mov_b32 s18, s39
	s_cbranch_scc0 .LBB0_106
	v_readlane_b32 s16, v254, 12
	v_readlane_b32 s17, v254, 13
	s_and_b64 vcc, exec, s[16:17]
	s_movk_i32 s37, 0x580
	s_cbranch_vccz .LBB0_109
	s_barrier

; #define STAGE(bufoff, GB) do { const char* g_ = (GB); \
;         _Pragma("unroll") for (int i_ = 0; i_ < 2; ++i_) __builtin_amdgcn_global_load_lds((const unsigned*)(g_ + voff[i_]), (LAS3 unsigned*)(L + (bufoff) + stoff + i_ * 8192), 16, 0, 0); } while (0)
; #define LDA(dst, b, h) do { _Pragma("unroll") for (int m = 0; m < 4; ++m) _Pragma("unroll") for (int k = 0; k < 2; ++k) dst[m][k] = *(const LAS3 bf16x8*)(L + SA(b, h) + aoff + m * 2048 + k * 1024); } while (0)
; #define LDB(dst, b, h) do { _Pragma("unroll") for (int n = 0; n < 2; ++n) _Pragma("unroll") for (int k = 0; k < 2; ++k) dst[n][k] = *(const LAS3 bf16x8*)(L + SB(b, h) + boff + n * 2048 + k * 1024); } while (0)
; #define WAIT_V(n) asm volatile("s_waitcnt vmcnt(" #n ")" ::: "memory")
; #define WAIT_L(n) asm volatile("s_waitcnt lgkmcnt(" #n ")" ::: "memory")
; #define BAR __builtin_amdgcn_s_barrier()
; #define SCHED __builtin_amdgcn_sched_barrier(0)
; template <int EPI>
; DI void gemm_phase(const bf16_t* __restrict__ A, const bf16_t* __restrict__ Bt, const int K, const int N, const Params& p, const int layer_j, char* lds) {
;     ...
;             LDA(At, 0, 1); STAGE(SB(0, 0), b2); STAGE(SB(0, 1), b2 + hstep); STAGE(SA(0, 0), a2);
;             WAIT_V(8); WAIT_L(0); BAR; MMA(1, 0, At, B0); MMA(1, 1, At, B1); BAR; SCHED;
;             LDB(B0, 1, 0); LDB(B1, 1, 1); SCHED; LDA(At, 1, 0); STAGE(SA(0, 1), a2 + hstep);
;             WAIT_V(8); WAIT_L(0); BAR; MMA(0, 0, At, B0); MMA(0, 1, At, B1); BAR; SCHED;
.Lskipw_rec_1:
	s_waitcnt lgkmcnt(0)
	s_barrier
	s_setprio 1
	s_waitcnt lgkmcnt(0)
	s_nop 0
	v_mfma_f32_16x16x32_bf16 v[70:73], v[136:139], v[168:171], v[70:73]
	v_mfma_f32_16x16x32_bf16 v[54:57], v[144:147], v[168:171], v[54:57]
	v_mfma_f32_16x16x32_bf16 v[66:69], v[136:139], v[176:179], v[66:69]
	v_mfma_f32_16x16x32_bf16 v[50:53], v[144:147], v[176:179], v[50:53]
	v_mfma_f32_16x16x32_bf16 v[62:65], v[136:139], v[212:215], v[62:65]
	v_mfma_f32_16x16x32_bf16 v[46:49], v[144:147], v[212:215], v[46:49]
	v_mfma_f32_16x16x32_bf16 v[58:61], v[136:139], v[220:223], v[58:61]
	v_mfma_f32_16x16x32_bf16 v[42:45], v[144:147], v[220:223], v[42:45]
	v_mfma_f32_16x16x32_bf16 v[70:73], v[140:143], v[172:175], v[70:73]
	v_mfma_f32_16x16x32_bf16 v[54:57], v[148:151], v[172:175], v[54:57]
	v_mfma_f32_16x16x32_bf16 v[66:69], v[140:143], v[180:183], v[66:69]
	v_mfma_f32_16x16x32_bf16 v[50:53], v[148:151], v[180:183], v[50:53]
	v_mfma_f32_16x16x32_bf16 v[62:65], v[140:143], v[216:219], v[62:65]
	v_mfma_f32_16x16x32_bf16 v[46:49], v[148:151], v[216:219], v[46:49]
	v_mfma_f32_16x16x32_bf16 v[58:61], v[140:143], v[224:227], v[58:61]
	v_mfma_f32_16x16x32_bf16 v[42:45], v[148:151], v[224:227], v[42:45]
	s_setprio 0
	s_setprio 1
	v_mfma_f32_16x16x32_bf16 v[34:37], v[152:155], v[168:171], v[34:37]
	v_mfma_f32_16x16x32_bf16 v[12:15], v[160:163], v[168:171], v[12:15]
	v_mfma_f32_16x16x32_bf16 v[28:31], v[152:155], v[176:179], v[28:31]
	v_mfma_f32_16x16x32_bf16 v[8:11], v[160:163], v[176:179], v[8:11]
	v_mfma_f32_16x16x32_bf16 v[24:27], v[152:155], v[212:215], v[24:27]
	v_mfma_f32_16x16x32_bf16 v[4:7], v[160:163], v[212:215], v[4:7]
	v_mfma_f32_16x16x32_bf16 v[20:23], v[152:155], v[220:223], v[20:23]
	v_mfma_f32_16x16x32_bf16 v[0:3], v[160:163], v[220:223], v[0:3]
	v_mfma_f32_16x16x32_bf16 v[34:37], v[156:159], v[172:175], v[34:37]
	v_mfma_f32_16x16x32_bf16 v[12:15], v[164:167], v[172:175], v[12:15]
	v_mfma_f32_16x16x32_bf16 v[28:31], v[156:159], v[180:183], v[28:31]
	v_mfma_f32_16x16x32_bf16 v[8:11], v[164:167], v[180:183], v[8:11]
	v_mfma_f32_16x16x32_bf16 v[24:27], v[156:159], v[216:219], v[24:27]
	v_mfma_f32_16x16x32_bf16 v[4:7], v[164:167], v[216:219], v[4:7]
	v_mfma_f32_16x16x32_bf16 v[20:23], v[156:159], v[224:227], v[20:23]
	v_mfma_f32_16x16x32_bf16 v[0:3], v[164:167], v[224:227], v[0:3]
	s_setprio 0
	s_barrier
	v_add_u32_e32 v148, 0x18000, v186
	v_add_u32_e32 v164, 0x1c000, v186
	ds_read_b128 v[136:139], v148
	ds_read_b128 v[140:143], v148 offset:1024
	ds_read_b128 v[144:147], v148 offset:2048
	ds_read_b128 v[148:151], v148 offset:3072
	ds_read_b128 v[152:155], v164
	ds_read_b128 v[156:159], v164 offset:1024
	ds_read_b128 v[160:163], v164 offset:2048
	ds_read_b128 v[164:167], v164 offset:3072
	s_add_u32 s16, s34, 0x40000
	s_addc_u32 s17, s35, 0
	v_readfirstlane_b32 s6, v204
	v_lshl_add_u64 v[234:235], s[16:17], 0, v[32:33]
	s_mov_b32 m0, s6
	v_readfirstlane_b32 s6, v205
	ds_read_b128 v[168:171], v185 offset:32768
	ds_read_b128 v[172:175], v185 offset:33792
	ds_read_b128 v[176:179], v185 offset:34816
	ds_read_b128 v[180:183], v185 offset:35840
	ds_read_b128 v[212:215], v185 offset:36864
	ds_read_b128 v[216:219], v185 offset:37888
	ds_read_b128 v[220:223], v185 offset:38912
	ds_read_b128 v[224:227], v185 offset:39936
	global_load_lds_dwordx4 v[234:235], off
	v_lshl_add_u64 v[234:235], s[16:17], 0, v[130:131]
	s_mov_b32 m0, s6
	s_nop 0
	global_load_lds_dwordx4 v[234:235], off
	s_waitcnt vmcnt(8)
	s_waitcnt lgkmcnt(0)
	s_barrier
	s_setprio 1
	s_waitcnt lgkmcnt(0)
	s_nop 0
	v_mfma_f32_16x16x32_bf16 v[126:129], v[136:139], v[168:171], v[126:129]
	v_mfma_f32_16x16x32_bf16 v[122:125], v[144:147], v[168:171], v[122:125]
	v_mfma_f32_16x16x32_bf16 v[110:113], v[136:139], v[176:179], v[110:113]
	v_mfma_f32_16x16x32_bf16 v[106:109], v[144:147], v[176:179], v[106:109]
	v_mfma_f32_16x16x32_bf16 v[94:97], v[136:139], v[212:215], v[94:97]
	v_mfma_f32_16x16x32_bf16 v[90:93], v[144:147], v[212:215], v[90:93]
	v_mfma_f32_16x16x32_bf16 v[78:81], v[136:139], v[220:223], v[78:81]
	v_mfma_f32_16x16x32_bf16 v[74:77], v[144:147], v[220:223], v[74:77]
	v_mfma_f32_16x16x32_bf16 v[126:129], v[140:143], v[172:175], v[126:129]
	v_mfma_f32_16x16x32_bf16 v[122:125], v[148:151], v[172:175], v[122:125]
	v_mfma_f32_16x16x32_bf16 v[110:113], v[140:143], v[180:183], v[110:113]
	v_mfma_f32_16x16x32_bf16 v[106:109], v[148:151], v[180:183], v[106:109]
	v_mfma_f32_16x16x32_bf16 v[94:97], v[140:143], v[216:219], v[94:97]
	v_mfma_f32_16x16x32_bf16 v[90:93], v[148:151], v[216:219], v[90:93]
	v_mfma_f32_16x16x32_bf16 v[78:81], v[140:143], v[224:227], v[78:81]
	v_mfma_f32_16x16x32_bf16 v[74:77], v[148:151], v[224:227], v[74:77]
	s_setprio 0
	s_setprio 1
	v_mfma_f32_16x16x32_bf16 v[118:121], v[152:155], v[168:171], v[118:121]
	v_mfma_f32_16x16x32_bf16 v[114:117], v[160:163], v[168:171], v[114:117]
	v_mfma_f32_16x16x32_bf16 v[102:105], v[152:155], v[176:179], v[102:105]
	v_mfma_f32_16x16x32_bf16 v[98:101], v[160:163], v[176:179], v[98:101]
	v_mfma_f32_16x16x32_bf16 v[86:89], v[152:155], v[212:215], v[86:89]
	v_mfma_f32_16x16x32_bf16 v[82:85], v[160:163], v[212:215], v[82:85]
	v_mfma_f32_16x16x32_bf16 v[38:41], v[152:155], v[220:223], v[38:41]
	v_mfma_f32_16x16x32_bf16 v[16:19], v[160:163], v[220:223], v[16:19]
	v_mfma_f32_16x16x32_bf16 v[118:121], v[156:159], v[172:175], v[118:121]
	v_mfma_f32_16x16x32_bf16 v[114:117], v[164:167], v[172:175], v[114:117]
	v_mfma_f32_16x16x32_bf16 v[102:105], v[156:159], v[180:183], v[102:105]
	v_mfma_f32_16x16x32_bf16 v[98:101], v[164:167], v[180:183], v[98:101]
	v_mfma_f32_16x16x32_bf16 v[86:89], v[156:159], v[216:219], v[86:89]
	v_mfma_f32_16x16x32_bf16 v[82:85], v[164:167], v[216:219], v[82:85]
	v_mfma_f32_16x16x32_bf16 v[38:41], v[156:159], v[224:227], v[38:41]
	v_mfma_f32_16x16x32_bf16 v[16:19], v[164:167], v[224:227], v[16:19]
	s_setprio 0
	s_barrier
; #define STAGE(bufoff, GB) do { const char* g_ = (GB); \
;         _Pragma("unroll") for (int i_ = 0; i_ < 2; ++i_) __builtin_amdgcn_global_load_lds((const unsigned*)(g_ + voff[i_]), (LAS3 unsigned*)(L + (bufoff) + stoff + i_ * 8192), 16, 0, 0); } while (0)
; #define LDA(dst, b, h) do { _Pragma("unroll") for (int m = 0; m < 4; ++m) _Pragma("unroll") for (int k = 0; k < 2; ++k) dst[m][k] = *(const LAS3 bf16x8*)(L + SA(b, h) + aoff + m * 2048 + k * 1024); } while (0)
; #define WAIT_V(n) asm volatile("s_waitcnt vmcnt(" #n ")" ::: "memory")
; #define WAIT_L(n) asm volatile("s_waitcnt lgkmcnt(" #n ")" ::: "memory")
; #define BAR __builtin_amdgcn_s_barrier()
; #define SCHED __builtin_amdgcn_sched_barrier(0)
; template <int EPI>
; DI void gemm_phase(const bf16_t* __restrict__ A, const bf16_t* __restrict__ Bt, const int K, const int N, const Params& p, const int layer_j, char* lds) {
;     ...
;             LDA(At, 1, 1); STAGE(SB(1, 0), b3); STAGE(SB(1, 1), b3 + hstep); STAGE(SA(1, 0), a3);
;             WAIT_V(8); WAIT_L(0); BAR; MMA(1, 0, At, B0); MMA(1, 1, At, B1); BAR; SCHED;
;         }
	v_readfirstlane_b32 s6, v206
	v_lshl_add_u64 v[194:195], v[194:195], 0, s[94:95]
	s_mov_b32 m0, s6
	v_readfirstlane_b32 s6, v207
	s_add_u32 s16, s30, 0x40080
	ds_read_b128 v[168:171], v185 offset:49152
	ds_read_b128 v[172:175], v185 offset:50176
	ds_read_b128 v[176:179], v185 offset:51200
	ds_read_b128 v[180:183], v185 offset:52224
	ds_read_b128 v[212:215], v185 offset:53248
	ds_read_b128 v[216:219], v185 offset:54272
	ds_read_b128 v[220:223], v185 offset:55296
	ds_read_b128 v[224:227], v185 offset:56320
	global_load_lds_dwordx4 v[194:195], off
	v_lshl_add_u64 v[194:195], v[228:229], 0, s[94:95]
	s_mov_b32 m0, s6
	s_addc_u32 s17, s31, 0
	v_readfirstlane_b32 s6, v210
	global_load_lds_dwordx4 v[194:195], off
	v_lshl_add_u64 v[194:195], s[16:17], 0, v[32:33]
	s_mov_b32 m0, s6
	v_readfirstlane_b32 s6, v211
	global_load_lds_dwordx4 v[194:195], off
	v_lshl_add_u64 v[194:195], s[16:17], 0, v[130:131]
	s_mov_b32 m0, s6
	v_readfirstlane_b32 s6, v208
	global_load_lds_dwordx4 v[194:195], off
	v_lshl_add_u64 v[194:195], v[230:231], 0, s[94:95]
	s_mov_b32 m0, s6
	v_readfirstlane_b32 s6, v209
	global_load_lds_dwordx4 v[194:195], off
	v_lshl_add_u64 v[194:195], v[232:233], 0, s[94:95]
	s_mov_b32 m0, s6
	s_nop 0
	global_load_lds_dwordx4 v[194:195], off
	s_waitcnt vmcnt(8)
	s_waitcnt lgkmcnt(0)
	s_barrier
	s_setprio 1
	s_waitcnt lgkmcnt(0)
	s_nop 0
	v_mfma_f32_16x16x32_bf16 v[70:73], v[136:139], v[168:171], v[70:73]
	v_mfma_f32_16x16x32_bf16 v[54:57], v[144:147], v[168:171], v[54:57]
	v_mfma_f32_16x16x32_bf16 v[66:69], v[136:139], v[176:179], v[66:69]
	v_mfma_f32_16x16x32_bf16 v[50:53], v[144:147], v[176:179], v[50:53]
	v_mfma_f32_16x16x32_bf16 v[62:65], v[136:139], v[212:215], v[62:65]
	v_mfma_f32_16x16x32_bf16 v[46:49], v[144:147], v[212:215], v[46:49]
	v_mfma_f32_16x16x32_bf16 v[58:61], v[136:139], v[220:223], v[58:61]
	v_mfma_f32_16x16x32_bf16 v[42:45], v[144:147], v[220:223], v[42:45]
	v_mfma_f32_16x16x32_bf16 v[70:73], v[140:143], v[172:175], v[70:73]
	v_mfma_f32_16x16x32_bf16 v[54:57], v[148:151], v[172:175], v[54:57]
	v_mfma_f32_16x16x32_bf16 v[66:69], v[140:143], v[180:183], v[66:69]
	v_mfma_f32_16x16x32_bf16 v[50:53], v[148:151], v[180:183], v[50:53]
	v_mfma_f32_16x16x32_bf16 v[62:65], v[140:143], v[216:219], v[62:65]
	v_mfma_f32_16x16x32_bf16 v[46:49], v[148:151], v[216:219], v[46:49]
	v_mfma_f32_16x16x32_bf16 v[58:61], v[140:143], v[224:227], v[58:61]
	v_mfma_f32_16x16x32_bf16 v[42:45], v[148:151], v[224:227], v[42:45]
	s_setprio 0
	s_setprio 1
	v_mfma_f32_16x16x32_bf16 v[34:37], v[152:155], v[168:171], v[34:37]
	v_mfma_f32_16x16x32_bf16 v[12:15], v[160:163], v[168:171], v[12:15]
	v_mfma_f32_16x16x32_bf16 v[28:31], v[152:155], v[176:179], v[28:31]
	v_mfma_f32_16x16x32_bf16 v[8:11], v[160:163], v[176:179], v[8:11]
	v_mfma_f32_16x16x32_bf16 v[24:27], v[152:155], v[212:215], v[24:27]
	v_mfma_f32_16x16x32_bf16 v[4:7], v[160:163], v[212:215], v[4:7]
	v_mfma_f32_16x16x32_bf16 v[20:23], v[152:155], v[220:223], v[20:23]
	v_mfma_f32_16x16x32_bf16 v[0:3], v[160:163], v[220:223], v[0:3]
	v_mfma_f32_16x16x32_bf16 v[34:37], v[156:159], v[172:175], v[34:37]
	v_mfma_f32_16x16x32_bf16 v[12:15], v[164:167], v[172:175], v[12:15]
	v_mfma_f32_16x16x32_bf16 v[28:31], v[156:159], v[180:183], v[28:31]
	v_mfma_f32_16x16x32_bf16 v[8:11], v[164:167], v[180:183], v[8:11]
	v_mfma_f32_16x16x32_bf16 v[24:27], v[156:159], v[216:219], v[24:27]
	v_mfma_f32_16x16x32_bf16 v[4:7], v[164:167], v[216:219], v[4:7]
	v_mfma_f32_16x16x32_bf16 v[20:23], v[156:159], v[224:227], v[20:23]
	v_mfma_f32_16x16x32_bf16 v[0:3], v[164:167], v[224:227], v[0:3]
	s_setprio 0
	s_barrier
	s_add_i32 vcc_lo, vcc_lo, 2
	s_add_u32 s28, s28, 0x100
	s_addc_u32 s29, s29, 0
	s_cmp_gt_u32 vcc_lo, 13
	s_cbranch_scc0 .LBB0_338
	s_branch .Lrec_kloop_done

; #define STAGE(bufoff, GB) do { const char* g_ = (GB); \
;         _Pragma("unroll") for (int i_ = 0; i_ < 2; ++i_) __builtin_amdgcn_global_load_lds((const unsigned*)(g_ + voff[i_]), (LAS3 unsigned*)(L + (bufoff) + stoff + i_ * 8192), 16, 0, 0); } while (0)
; #define LDA(dst, b, h) do { _Pragma("unroll") for (int m = 0; m < 4; ++m) _Pragma("unroll") for (int k = 0; k < 2; ++k) dst[m][k] = *(const LAS3 bf16x8*)(L + SA(b, h) + aoff + m * 2048 + k * 1024); } while (0)
; #define WAIT_V(n) asm volatile("s_waitcnt vmcnt(" #n ")" ::: "memory")
; #define WAIT_L(n) asm volatile("s_waitcnt lgkmcnt(" #n ")" ::: "memory")
; #define BAR __builtin_amdgcn_s_barrier()
; #define SCHED __builtin_amdgcn_sched_barrier(0)
; template <int EPI>
; DI void gemm_phase(const bf16_t* __restrict__ A, const bf16_t* __restrict__ Bt, const int K, const int N, const Params& p, const int layer_j, char* lds) {
;     ...
;             WAIT_V(8); WAIT_L(0); BAR; MMA(0, 0, At, B0); MMA(0, 1, At, B1); BAR; SCHED;
;             LDA(At, 0, 1); STAGE(SB(0, 0), b2); STAGE(SB(0, 1), b2 + hstep); STAGE(SA(0, 0), a2);
;             WAIT_V(8); WAIT_L(0); BAR; MMA(1, 0, At, B0); MMA(1, 1, At, B1); BAR; SCHED;
.Lskipw_recns_0:
	s_waitcnt lgkmcnt(0)
	s_barrier
	s_setprio 1
	s_waitcnt lgkmcnt(0)
	s_nop 0
	v_mfma_f32_16x16x32_bf16 v[126:129], v[168:171], v[136:139], v[126:129]
	v_mfma_f32_16x16x32_bf16 v[122:125], v[168:171], v[144:147], v[122:125]
	v_mfma_f32_16x16x32_bf16 v[110:113], v[176:179], v[136:139], v[110:113]
	v_mfma_f32_16x16x32_bf16 v[106:109], v[176:179], v[144:147], v[106:109]
	v_mfma_f32_16x16x32_bf16 v[94:97], v[212:215], v[136:139], v[94:97]
	v_mfma_f32_16x16x32_bf16 v[90:93], v[212:215], v[144:147], v[90:93]
	v_mfma_f32_16x16x32_bf16 v[78:81], v[220:223], v[136:139], v[78:81]
	v_mfma_f32_16x16x32_bf16 v[74:77], v[220:223], v[144:147], v[74:77]
	v_mfma_f32_16x16x32_bf16 v[126:129], v[172:175], v[140:143], v[126:129]
	v_mfma_f32_16x16x32_bf16 v[122:125], v[172:175], v[148:151], v[122:125]
	v_mfma_f32_16x16x32_bf16 v[110:113], v[180:183], v[140:143], v[110:113]
	v_mfma_f32_16x16x32_bf16 v[106:109], v[180:183], v[148:151], v[106:109]
	v_mfma_f32_16x16x32_bf16 v[94:97], v[216:219], v[140:143], v[94:97]
	v_mfma_f32_16x16x32_bf16 v[90:93], v[216:219], v[148:151], v[90:93]
	v_mfma_f32_16x16x32_bf16 v[78:81], v[224:227], v[140:143], v[78:81]
	v_mfma_f32_16x16x32_bf16 v[74:77], v[224:227], v[148:151], v[74:77]
	s_setprio 0
	s_setprio 1
	v_mfma_f32_16x16x32_bf16 v[118:121], v[168:171], v[152:155], v[118:121]
	v_mfma_f32_16x16x32_bf16 v[114:117], v[168:171], v[160:163], v[114:117]
	v_mfma_f32_16x16x32_bf16 v[102:105], v[176:179], v[152:155], v[102:105]
	v_mfma_f32_16x16x32_bf16 v[98:101], v[176:179], v[160:163], v[98:101]
	v_mfma_f32_16x16x32_bf16 v[86:89], v[212:215], v[152:155], v[86:89]
	v_mfma_f32_16x16x32_bf16 v[82:85], v[212:215], v[160:163], v[82:85]
	v_mfma_f32_16x16x32_bf16 v[38:41], v[220:223], v[152:155], v[38:41]
	v_mfma_f32_16x16x32_bf16 v[16:19], v[220:223], v[160:163], v[16:19]
	v_mfma_f32_16x16x32_bf16 v[118:121], v[172:175], v[156:159], v[118:121]
	v_mfma_f32_16x16x32_bf16 v[114:117], v[172:175], v[164:167], v[114:117]
	v_mfma_f32_16x16x32_bf16 v[102:105], v[180:183], v[156:159], v[102:105]
	v_mfma_f32_16x16x32_bf16 v[98:101], v[180:183], v[164:167], v[98:101]
	v_mfma_f32_16x16x32_bf16 v[86:89], v[216:219], v[156:159], v[86:89]
	v_mfma_f32_16x16x32_bf16 v[82:85], v[216:219], v[164:167], v[82:85]
	v_mfma_f32_16x16x32_bf16 v[38:41], v[224:227], v[156:159], v[38:41]
	v_mfma_f32_16x16x32_bf16 v[16:19], v[224:227], v[164:167], v[16:19]
	s_setprio 0
	s_barrier
	v_readfirstlane_b32 s16, v187
	v_lshl_add_u64 v[194:195], s[30:31], 0, v[32:33]
	s_mov_b32 m0, s16
	v_readfirstlane_b32 s16, v188
	ds_read_b128 v[168:171], v185 offset:16384
	ds_read_b128 v[172:175], v185 offset:17408
	ds_read_b128 v[176:179], v185 offset:18432
	ds_read_b128 v[180:183], v185 offset:19456
	ds_read_b128 v[212:215], v185 offset:20480
	ds_read_b128 v[216:219], v185 offset:21504
	ds_read_b128 v[220:223], v185 offset:22528
	ds_read_b128 v[224:227], v185 offset:23552
	global_load_lds_dwordx4 v[194:195], off
	s_mov_b32 m0, s16
	s_add_u32 s16, s30, 0x40000
	v_lshl_add_u64 v[228:229], s[30:31], 0, v[130:131]
	s_addc_u32 s17, s31, 0
	v_readfirstlane_b32 s6, v189
	global_load_lds_dwordx4 v[228:229], off
	v_lshl_add_u64 v[230:231], s[16:17], 0, v[32:33]
	s_mov_b32 m0, s6
	v_readfirstlane_b32 s6, v190
	global_load_lds_dwordx4 v[230:231], off
	v_lshl_add_u64 v[230:231], s[16:17], 0, v[130:131]
	s_mov_b32 m0, s6
	v_readfirstlane_b32 s6, v184
	global_load_lds_dwordx4 v[230:231], off
	v_lshl_add_u64 v[230:231], s[34:35], 0, v[32:33]
	s_mov_b32 m0, s6
	v_readfirstlane_b32 s6, v191
	global_load_lds_dwordx4 v[230:231], off
	v_lshl_add_u64 v[232:233], s[34:35], 0, v[130:131]
	s_mov_b32 m0, s6
	s_nop 0
	global_load_lds_dwordx4 v[232:233], off
	s_cmp_eq_u32 s101, 0
	s_cbranch_scc1 .Lskipw_recns_1
	s_waitcnt vmcnt(8)
.Lskipw_recns_1:
	s_waitcnt lgkmcnt(0)
	s_barrier
	s_setprio 1
	s_waitcnt lgkmcnt(0)
	s_nop 0
	v_mfma_f32_16x16x32_bf16 v[70:73], v[168:171], v[136:139], v[70:73]
	v_mfma_f32_16x16x32_bf16 v[54:57], v[168:171], v[144:147], v[54:57]
	v_mfma_f32_16x16x32_bf16 v[66:69], v[176:179], v[136:139], v[66:69]
	v_mfma_f32_16x16x32_bf16 v[50:53], v[176:179], v[144:147], v[50:53]
	v_mfma_f32_16x16x32_bf16 v[62:65], v[212:215], v[136:139], v[62:65]
	v_mfma_f32_16x16x32_bf16 v[46:49], v[212:215], v[144:147], v[46:49]
	v_mfma_f32_16x16x32_bf16 v[58:61], v[220:223], v[136:139], v[58:61]
	v_mfma_f32_16x16x32_bf16 v[42:45], v[220:223], v[144:147], v[42:45]
	v_mfma_f32_16x16x32_bf16 v[70:73], v[172:175], v[140:143], v[70:73]
	v_mfma_f32_16x16x32_bf16 v[54:57], v[172:175], v[148:151], v[54:57]
	v_mfma_f32_16x16x32_bf16 v[66:69], v[180:183], v[140:143], v[66:69]
	v_mfma_f32_16x16x32_bf16 v[50:53], v[180:183], v[148:151], v[50:53]
	v_mfma_f32_16x16x32_bf16 v[62:65], v[216:219], v[140:143], v[62:65]
	v_mfma_f32_16x16x32_bf16 v[46:49], v[216:219], v[148:151], v[46:49]
	v_mfma_f32_16x16x32_bf16 v[58:61], v[224:227], v[140:143], v[58:61]
	v_mfma_f32_16x16x32_bf16 v[42:45], v[224:227], v[148:151], v[42:45]
	s_setprio 0
	s_setprio 1
	v_mfma_f32_16x16x32_bf16 v[34:37], v[168:171], v[152:155], v[34:37]
	v_mfma_f32_16x16x32_bf16 v[12:15], v[168:171], v[160:163], v[12:15]
	v_mfma_f32_16x16x32_bf16 v[28:31], v[176:179], v[152:155], v[28:31]
	v_mfma_f32_16x16x32_bf16 v[8:11], v[176:179], v[160:163], v[8:11]
	v_mfma_f32_16x16x32_bf16 v[24:27], v[212:215], v[152:155], v[24:27]
	v_mfma_f32_16x16x32_bf16 v[4:7], v[212:215], v[160:163], v[4:7]
	v_mfma_f32_16x16x32_bf16 v[20:23], v[220:223], v[152:155], v[20:23]
	v_mfma_f32_16x16x32_bf16 v[0:3], v[220:223], v[160:163], v[0:3]
	v_mfma_f32_16x16x32_bf16 v[34:37], v[172:175], v[156:159], v[34:37]
	v_mfma_f32_16x16x32_bf16 v[12:15], v[172:175], v[164:167], v[12:15]
	v_mfma_f32_16x16x32_bf16 v[28:31], v[180:183], v[156:159], v[28:31]
	v_mfma_f32_16x16x32_bf16 v[8:11], v[180:183], v[164:167], v[8:11]
	v_mfma_f32_16x16x32_bf16 v[24:27], v[216:219], v[156:159], v[24:27]
	v_mfma_f32_16x16x32_bf16 v[4:7], v[216:219], v[164:167], v[4:7]
	v_mfma_f32_16x16x32_bf16 v[20:23], v[224:227], v[156:159], v[20:23]
	v_mfma_f32_16x16x32_bf16 v[0:3], v[224:227], v[164:167], v[0:3]
	s_setprio 0
	s_barrier
; #define STAGE(bufoff, GB) do { const char* g_ = (GB); \
;         _Pragma("unroll") for (int i_ = 0; i_ < 2; ++i_) __builtin_amdgcn_global_load_lds((const unsigned*)(g_ + voff[i_]), (LAS3 unsigned*)(L + (bufoff) + stoff + i_ * 8192), 16, 0, 0); } while (0)
; #define LDA(dst, b, h) do { _Pragma("unroll") for (int m = 0; m < 4; ++m) _Pragma("unroll") for (int k = 0; k < 2; ++k) dst[m][k] = *(const LAS3 bf16x8*)(L + SA(b, h) + aoff + m * 2048 + k * 1024); } while (0)
; #define LDB(dst, b, h) do { _Pragma("unroll") for (int n = 0; n < 2; ++n) _Pragma("unroll") for (int k = 0; k < 2; ++k) dst[n][k] = *(const LAS3 bf16x8*)(L + SB(b, h) + boff + n * 2048 + k * 1024); } while (0)
; #define WAIT_V(n) asm volatile("s_waitcnt vmcnt(" #n ")" ::: "memory")
; #define WAIT_L(n) asm volatile("s_waitcnt lgkmcnt(" #n ")" ::: "memory")
; #define BAR __builtin_amdgcn_s_barrier()
; #define SCHED __builtin_amdgcn_sched_barrier(0)
; template <int EPI>
; DI void gemm_phase(const bf16_t* __restrict__ A, const bf16_t* __restrict__ Bt, const int K, const int N, const Params& p, const int layer_j, char* lds) {
;     ...
;             LDB(B0, 1, 0); LDB(B1, 1, 1); SCHED; LDA(At, 1, 0); STAGE(SA(0, 1), a2 + hstep);
;             WAIT_V(8); WAIT_L(0); BAR; MMA(0, 0, At, B0); MMA(0, 1, At, B1); BAR; SCHED;
	v_add_u32_e32 v148, 0x18000, v186
	v_add_u32_e32 v164, 0x1c000, v186
	ds_read_b128 v[136:139], v148
	ds_read_b128 v[140:143], v148 offset:1024
	ds_read_b128 v[144:147], v148 offset:2048
	ds_read_b128 v[148:151], v148 offset:3072
	ds_read_b128 v[152:155], v164
	ds_read_b128 v[156:159], v164 offset:1024
	ds_read_b128 v[160:163], v164 offset:2048
	ds_read_b128 v[164:167], v164 offset:3072
	s_add_u32 s16, s34, 0x40000
	s_addc_u32 s17, s35, 0
	v_readfirstlane_b32 s6, v204
	v_lshl_add_u64 v[234:235], s[16:17], 0, v[32:33]
	s_mov_b32 m0, s6
	v_readfirstlane_b32 s6, v205
	ds_read_b128 v[168:171], v185 offset:32768
	ds_read_b128 v[172:175], v185 offset:33792
	ds_read_b128 v[176:179], v185 offset:34816
	ds_read_b128 v[180:183], v185 offset:35840
	ds_read_b128 v[212:215], v185 offset:36864
	ds_read_b128 v[216:219], v185 offset:37888
	ds_read_b128 v[220:223], v185 offset:38912
	ds_read_b128 v[224:227], v185 offset:39936
	global_load_lds_dwordx4 v[234:235], off
	v_lshl_add_u64 v[234:235], s[16:17], 0, v[130:131]
	s_mov_b32 m0, s6
	s_nop 0
	global_load_lds_dwordx4 v[234:235], off
	s_waitcnt vmcnt(8)
	s_waitcnt lgkmcnt(0)
	s_barrier
	s_setprio 1
	s_waitcnt lgkmcnt(0)
	s_nop 0
	v_mfma_f32_16x16x32_bf16 v[126:129], v[168:171], v[136:139], v[126:129]
	v_mfma_f32_16x16x32_bf16 v[122:125], v[168:171], v[144:147], v[122:125]
	v_mfma_f32_16x16x32_bf16 v[110:113], v[176:179], v[136:139], v[110:113]
	v_mfma_f32_16x16x32_bf16 v[106:109], v[176:179], v[144:147], v[106:109]
	v_mfma_f32_16x16x32_bf16 v[94:97], v[212:215], v[136:139], v[94:97]
	v_mfma_f32_16x16x32_bf16 v[90:93], v[212:215], v[144:147], v[90:93]
	v_mfma_f32_16x16x32_bf16 v[78:81], v[220:223], v[136:139], v[78:81]
	v_mfma_f32_16x16x32_bf16 v[74:77], v[220:223], v[144:147], v[74:77]
	v_mfma_f32_16x16x32_bf16 v[126:129], v[172:175], v[140:143], v[126:129]
	v_mfma_f32_16x16x32_bf16 v[122:125], v[172:175], v[148:151], v[122:125]
	v_mfma_f32_16x16x32_bf16 v[110:113], v[180:183], v[140:143], v[110:113]
	v_mfma_f32_16x16x32_bf16 v[106:109], v[180:183], v[148:151], v[106:109]
	v_mfma_f32_16x16x32_bf16 v[94:97], v[216:219], v[140:143], v[94:97]
	v_mfma_f32_16x16x32_bf16 v[90:93], v[216:219], v[148:151], v[90:93]
	v_mfma_f32_16x16x32_bf16 v[78:81], v[224:227], v[140:143], v[78:81]
	v_mfma_f32_16x16x32_bf16 v[74:77], v[224:227], v[148:151], v[74:77]
	s_setprio 0
	s_setprio 1
	v_mfma_f32_16x16x32_bf16 v[118:121], v[168:171], v[152:155], v[118:121]
	v_mfma_f32_16x16x32_bf16 v[114:117], v[168:171], v[160:163], v[114:117]
	v_mfma_f32_16x16x32_bf16 v[102:105], v[176:179], v[152:155], v[102:105]
	v_mfma_f32_16x16x32_bf16 v[98:101], v[176:179], v[160:163], v[98:101]
	v_mfma_f32_16x16x32_bf16 v[86:89], v[212:215], v[152:155], v[86:89]
	v_mfma_f32_16x16x32_bf16 v[82:85], v[212:215], v[160:163], v[82:85]
	v_mfma_f32_16x16x32_bf16 v[38:41], v[220:223], v[152:155], v[38:41]
	v_mfma_f32_16x16x32_bf16 v[16:19], v[220:223], v[160:163], v[16:19]
	v_mfma_f32_16x16x32_bf16 v[118:121], v[172:175], v[156:159], v[118:121]
	v_mfma_f32_16x16x32_bf16 v[114:117], v[172:175], v[164:167], v[114:117]
	v_mfma_f32_16x16x32_bf16 v[102:105], v[180:183], v[156:159], v[102:105]
	v_mfma_f32_16x16x32_bf16 v[98:101], v[180:183], v[164:167], v[98:101]
	v_mfma_f32_16x16x32_bf16 v[86:89], v[216:219], v[156:159], v[86:89]
	v_mfma_f32_16x16x32_bf16 v[82:85], v[216:219], v[164:167], v[82:85]
	v_mfma_f32_16x16x32_bf16 v[38:41], v[224:227], v[156:159], v[38:41]
	v_mfma_f32_16x16x32_bf16 v[16:19], v[224:227], v[164:167], v[16:19]
	s_setprio 0
	s_barrier
; #define STAGE(bufoff, GB) do { const char* g_ = (GB); \
;         _Pragma("unroll") for (int i_ = 0; i_ < 2; ++i_) __builtin_amdgcn_global_load_lds((const unsigned*)(g_ + voff[i_]), (LAS3 unsigned*)(L + (bufoff) + stoff + i_ * 8192), 16, 0, 0); } while (0)
; #define LDA(dst, b, h) do { _Pragma("unroll") for (int m = 0; m < 4; ++m) _Pragma("unroll") for (int k = 0; k < 2; ++k) dst[m][k] = *(const LAS3 bf16x8*)(L + SA(b, h) + aoff + m * 2048 + k * 1024); } while (0)
; #define WAIT_V(n) asm volatile("s_waitcnt vmcnt(" #n ")" ::: "memory")
; #define WAIT_L(n) asm volatile("s_waitcnt lgkmcnt(" #n ")" ::: "memory")
; #define BAR __builtin_amdgcn_s_barrier()
; #define SCHED __builtin_amdgcn_sched_barrier(0)
; template <int EPI>
; DI void gemm_phase(const bf16_t* __restrict__ A, const bf16_t* __restrict__ Bt, const int K, const int N, const Params& p, const int layer_j, char* lds) {
;     ...
;             LDA(At, 1, 1); STAGE(SB(1, 0), b3); STAGE(SB(1, 1), b3 + hstep); STAGE(SA(1, 0), a3);
;             WAIT_V(8); WAIT_L(0); BAR; MMA(1, 0, At, B0); MMA(1, 1, At, B1); BAR; SCHED;
;         }
	v_readfirstlane_b32 s6, v206
	v_lshl_add_u64 v[194:195], v[194:195], 0, s[94:95]
	s_mov_b32 m0, s6
	v_readfirstlane_b32 s6, v207
	s_add_u32 s16, s30, 0x40080
	ds_read_b128 v[168:171], v185 offset:49152
	ds_read_b128 v[172:175], v185 offset:50176
	ds_read_b128 v[176:179], v185 offset:51200
	ds_read_b128 v[180:183], v185 offset:52224
	ds_read_b128 v[212:215], v185 offset:53248
	ds_read_b128 v[216:219], v185 offset:54272
	ds_read_b128 v[220:223], v185 offset:55296
	ds_read_b128 v[224:227], v185 offset:56320
	global_load_lds_dwordx4 v[194:195], off
	v_lshl_add_u64 v[194:195], v[228:229], 0, s[94:95]
	s_mov_b32 m0, s6
	s_addc_u32 s17, s31, 0
	v_readfirstlane_b32 s6, v210
	global_load_lds_dwordx4 v[194:195], off
	v_lshl_add_u64 v[194:195], s[16:17], 0, v[32:33]
	s_mov_b32 m0, s6
	v_readfirstlane_b32 s6, v211
	global_load_lds_dwordx4 v[194:195], off
	v_lshl_add_u64 v[194:195], s[16:17], 0, v[130:131]
	s_mov_b32 m0, s6
	v_readfirstlane_b32 s6, v208
	global_load_lds_dwordx4 v[194:195], off
	v_lshl_add_u64 v[194:195], v[230:231], 0, s[94:95]
	s_mov_b32 m0, s6
	v_readfirstlane_b32 s6, v209
	global_load_lds_dwordx4 v[194:195], off
	v_lshl_add_u64 v[194:195], v[232:233], 0, s[94:95]
	s_mov_b32 m0, s6
	s_nop 0
	global_load_lds_dwordx4 v[194:195], off
	s_waitcnt vmcnt(8)
	s_waitcnt lgkmcnt(0)
	s_barrier
	s_setprio 1
	s_waitcnt lgkmcnt(0)
	s_nop 0
	v_mfma_f32_16x16x32_bf16 v[70:73], v[168:171], v[136:139], v[70:73]
	v_mfma_f32_16x16x32_bf16 v[54:57], v[168:171], v[144:147], v[54:57]
	v_mfma_f32_16x16x32_bf16 v[66:69], v[176:179], v[136:139], v[66:69]
	v_mfma_f32_16x16x32_bf16 v[50:53], v[176:179], v[144:147], v[50:53]
	v_mfma_f32_16x16x32_bf16 v[62:65], v[212:215], v[136:139], v[62:65]
	v_mfma_f32_16x16x32_bf16 v[46:49], v[212:215], v[144:147], v[46:49]
	v_mfma_f32_16x16x32_bf16 v[58:61], v[220:223], v[136:139], v[58:61]
	v_mfma_f32_16x16x32_bf16 v[42:45], v[220:223], v[144:147], v[42:45]
	v_mfma_f32_16x16x32_bf16 v[70:73], v[172:175], v[140:143], v[70:73]
	v_mfma_f32_16x16x32_bf16 v[54:57], v[172:175], v[148:151], v[54:57]
	v_mfma_f32_16x16x32_bf16 v[66:69], v[180:183], v[140:143], v[66:69]
	v_mfma_f32_16x16x32_bf16 v[50:53], v[180:183], v[148:151], v[50:53]
	v_mfma_f32_16x16x32_bf16 v[62:65], v[216:219], v[140:143], v[62:65]
	v_mfma_f32_16x16x32_bf16 v[46:49], v[216:219], v[148:151], v[46:49]
	v_mfma_f32_16x16x32_bf16 v[58:61], v[224:227], v[140:143], v[58:61]
	v_mfma_f32_16x16x32_bf16 v[42:45], v[224:227], v[148:151], v[42:45]
	s_setprio 0
	s_setprio 1
	v_mfma_f32_16x16x32_bf16 v[34:37], v[168:171], v[152:155], v[34:37]
	v_mfma_f32_16x16x32_bf16 v[12:15], v[168:171], v[160:163], v[12:15]
	v_mfma_f32_16x16x32_bf16 v[28:31], v[176:179], v[152:155], v[28:31]
	v_mfma_f32_16x16x32_bf16 v[8:11], v[176:179], v[160:163], v[8:11]
	v_mfma_f32_16x16x32_bf16 v[24:27], v[212:215], v[152:155], v[24:27]
	v_mfma_f32_16x16x32_bf16 v[4:7], v[212:215], v[160:163], v[4:7]
	v_mfma_f32_16x16x32_bf16 v[20:23], v[220:223], v[152:155], v[20:23]
	v_mfma_f32_16x16x32_bf16 v[0:3], v[220:223], v[160:163], v[0:3]
	v_mfma_f32_16x16x32_bf16 v[34:37], v[172:175], v[156:159], v[34:37]
	v_mfma_f32_16x16x32_bf16 v[12:15], v[172:175], v[164:167], v[12:15]
	v_mfma_f32_16x16x32_bf16 v[28:31], v[180:183], v[156:159], v[28:31]
	v_mfma_f32_16x16x32_bf16 v[8:11], v[180:183], v[164:167], v[8:11]
	v_mfma_f32_16x16x32_bf16 v[24:27], v[216:219], v[156:159], v[24:27]
	v_mfma_f32_16x16x32_bf16 v[4:7], v[216:219], v[164:167], v[4:7]
	v_mfma_f32_16x16x32_bf16 v[20:23], v[224:227], v[156:159], v[20:23]
	v_mfma_f32_16x16x32_bf16 v[0:3], v[224:227], v[164:167], v[0:3]
	s_setprio 0
	s_barrier
	s_add_i32 vcc_lo, vcc_lo, 2
	s_add_u32 s28, s28, 0x100
	s_addc_u32 s29, s29, 0
	s_cmp_gt_u32 vcc_lo, 13
	s_cbranch_scc0 .Lrec_kloop_ns

; #define STAGE(bufoff, GB) do { const char* g_ = (GB); \
;         _Pragma("unroll") for (int i_ = 0; i_ < 2; ++i_) __builtin_amdgcn_global_load_lds((const unsigned*)(g_ + voff[i_]), (LAS3 unsigned*)(L + (bufoff) + stoff + i_ * 8192), 16, 0, 0); } while (0)
; #define LDA(dst, b, h) do { _Pragma("unroll") for (int m = 0; m < 4; ++m) _Pragma("unroll") for (int k = 0; k < 2; ++k) dst[m][k] = *(const LAS3 bf16x8*)(L + SA(b, h) + aoff + m * 2048 + k * 1024); } while (0)
; #define LDB(dst, b, h) do { _Pragma("unroll") for (int n = 0; n < 2; ++n) _Pragma("unroll") for (int k = 0; k < 2; ++k) dst[n][k] = *(const LAS3 bf16x8*)(L + SB(b, h) + boff + n * 2048 + k * 1024); } while (0)
; #define WAIT_V(n) asm volatile("s_waitcnt vmcnt(" #n ")" ::: "memory")
; #define WAIT_L(n) asm volatile("s_waitcnt lgkmcnt(" #n ")" ::: "memory")
; #define BAR __builtin_amdgcn_s_barrier()
; #define SCHED __builtin_amdgcn_sched_barrier(0)
; template <int EPI>
; DI void gemm_phase(const bf16_t* __restrict__ A, const bf16_t* __restrict__ Bt, const int K, const int N, const Params& p, const int layer_j, char* lds) {
;     ...
;             LDA(At, 0, 1); STAGE(SB(0, 0), b2); STAGE(SB(0, 1), b2 + hstep); STAGE(SA(0, 0), a2);
;             WAIT_V(8); WAIT_L(0); BAR; MMA(1, 0, At, B0); MMA(1, 1, At, B1); BAR; SCHED;
;             LDB(B0, 1, 0); LDB(B1, 1, 1); SCHED; LDA(At, 1, 0); STAGE(SA(0, 1), a2 + hstep);
;             WAIT_V(8); WAIT_L(0); BAR; MMA(0, 0, At, B0); MMA(0, 1, At, B1); BAR; SCHED;
.Lskipw_att_1:
	s_waitcnt lgkmcnt(0)
	s_barrier
	s_setprio 1
	s_waitcnt lgkmcnt(0)
	s_nop 0
	v_mfma_f32_16x16x32_bf16 v[98:101], v[154:157], v[186:189], v[98:101]
	v_mfma_f32_16x16x32_bf16 v[66:69], v[162:165], v[186:189], v[66:69]
	v_mfma_f32_16x16x32_bf16 v[90:93], v[154:157], v[208:211], v[90:93]
	v_mfma_f32_16x16x32_bf16 v[58:61], v[162:165], v[208:211], v[58:61]
	v_mfma_f32_16x16x32_bf16 v[86:89], v[154:157], v[216:219], v[86:89]
	v_mfma_f32_16x16x32_bf16 v[42:45], v[162:165], v[216:219], v[42:45]
	v_mfma_f32_16x16x32_bf16 v[70:73], v[154:157], v[224:227], v[70:73]
	v_mfma_f32_16x16x32_bf16 v[28:31], v[162:165], v[224:227], v[28:31]
	v_mfma_f32_16x16x32_bf16 v[98:101], v[158:161], v[204:207], v[98:101]
	v_mfma_f32_16x16x32_bf16 v[66:69], v[166:169], v[204:207], v[66:69]
	v_mfma_f32_16x16x32_bf16 v[90:93], v[158:161], v[212:215], v[90:93]
	v_mfma_f32_16x16x32_bf16 v[58:61], v[166:169], v[212:215], v[58:61]
	v_mfma_f32_16x16x32_bf16 v[86:89], v[158:161], v[220:223], v[86:89]
	v_mfma_f32_16x16x32_bf16 v[42:45], v[166:169], v[220:223], v[42:45]
	v_mfma_f32_16x16x32_bf16 v[70:73], v[158:161], v[228:231], v[70:73]
	v_mfma_f32_16x16x32_bf16 v[28:31], v[166:169], v[228:231], v[28:31]
	s_setprio 0
	s_setprio 1
	v_mfma_f32_16x16x32_bf16 v[16:19], v[170:173], v[186:189], v[16:19]
	v_mfma_f32_16x16x32_bf16 v[4:7], v[178:181], v[186:189], v[4:7]
	v_mfma_f32_16x16x32_bf16 v[8:11], v[170:173], v[208:211], v[8:11]
	v_mfma_f32_16x16x32_bf16 v[0:3], v[178:181], v[208:211], v[0:3]
	v_mfma_f32_16x16x32_bf16 v[78:81], v[170:173], v[216:219], v[78:81]
	v_mfma_f32_16x16x32_bf16 v[46:49], v[178:181], v[216:219], v[46:49]
	v_mfma_f32_16x16x32_bf16 v[82:85], v[170:173], v[224:227], v[82:85]
	v_mfma_f32_16x16x32_bf16 v[50:53], v[178:181], v[224:227], v[50:53]
	v_mfma_f32_16x16x32_bf16 v[16:19], v[174:177], v[204:207], v[16:19]
	v_mfma_f32_16x16x32_bf16 v[4:7], v[182:185], v[204:207], v[4:7]
	v_mfma_f32_16x16x32_bf16 v[8:11], v[174:177], v[212:215], v[8:11]
	v_mfma_f32_16x16x32_bf16 v[0:3], v[182:185], v[212:215], v[0:3]
	v_mfma_f32_16x16x32_bf16 v[78:81], v[174:177], v[220:223], v[78:81]
	v_mfma_f32_16x16x32_bf16 v[46:49], v[182:185], v[220:223], v[46:49]
	v_mfma_f32_16x16x32_bf16 v[82:85], v[174:177], v[228:231], v[82:85]
	v_mfma_f32_16x16x32_bf16 v[50:53], v[182:185], v[228:231], v[50:53]
	s_setprio 0
	s_barrier
	v_add_u32_e32 v166, 0x18000, v140
	v_add_u32_e32 v182, 0x1c000, v140
	ds_read_b128 v[154:157], v166
	ds_read_b128 v[158:161], v166 offset:1024
	ds_read_b128 v[162:165], v166 offset:2048
	ds_read_b128 v[166:169], v166 offset:3072
	ds_read_b128 v[170:173], v182
	ds_read_b128 v[174:177], v182 offset:1024
	ds_read_b128 v[178:181], v182 offset:2048
	ds_read_b128 v[182:185], v182 offset:3072
	s_add_u32 s30, s30, 0x40000
	s_addc_u32 s31, s31, 0
	v_readfirstlane_b32 s88, v146
	v_lshl_add_u64 v[234:235], s[30:31], 0, v[32:33]
	s_mov_b32 m0, s88
	ds_read_b128 v[186:189], v139 offset:32768
	ds_read_b128 v[204:207], v139 offset:33792
	ds_read_b128 v[208:211], v139 offset:34816
	ds_read_b128 v[212:215], v139 offset:35840
	ds_read_b128 v[216:219], v139 offset:36864
	ds_read_b128 v[220:223], v139 offset:37888
	ds_read_b128 v[224:227], v139 offset:38912
	ds_read_b128 v[228:231], v139 offset:39936
	global_load_lds_dwordx4 v[234:235], off
	v_lshl_add_u64 v[234:235], s[30:31], 0, v[130:131]
	v_readfirstlane_b32 s30, v147
	s_mov_b32 m0, s30
	s_nop 0
	global_load_lds_dwordx4 v[234:235], off
	s_waitcnt vmcnt(8)
	s_waitcnt lgkmcnt(0)
	s_barrier
	s_setprio 1
	s_waitcnt lgkmcnt(0)
	s_nop 0
	v_mfma_f32_16x16x32_bf16 v[126:129], v[154:157], v[186:189], v[126:129]
	v_mfma_f32_16x16x32_bf16 v[110:113], v[162:165], v[186:189], v[110:113]
	v_mfma_f32_16x16x32_bf16 v[122:125], v[154:157], v[208:211], v[122:125]
	v_mfma_f32_16x16x32_bf16 v[106:109], v[162:165], v[208:211], v[106:109]
	v_mfma_f32_16x16x32_bf16 v[118:121], v[154:157], v[216:219], v[118:121]
	v_mfma_f32_16x16x32_bf16 v[102:105], v[162:165], v[216:219], v[102:105]
	v_mfma_f32_16x16x32_bf16 v[114:117], v[154:157], v[224:227], v[114:117]
	v_mfma_f32_16x16x32_bf16 v[94:97], v[162:165], v[224:227], v[94:97]
	v_mfma_f32_16x16x32_bf16 v[126:129], v[158:161], v[204:207], v[126:129]
	v_mfma_f32_16x16x32_bf16 v[110:113], v[166:169], v[204:207], v[110:113]
	v_mfma_f32_16x16x32_bf16 v[122:125], v[158:161], v[212:215], v[122:125]
	v_mfma_f32_16x16x32_bf16 v[106:109], v[166:169], v[212:215], v[106:109]
	v_mfma_f32_16x16x32_bf16 v[118:121], v[158:161], v[220:223], v[118:121]
	v_mfma_f32_16x16x32_bf16 v[102:105], v[166:169], v[220:223], v[102:105]
	v_mfma_f32_16x16x32_bf16 v[114:117], v[158:161], v[228:231], v[114:117]
	v_mfma_f32_16x16x32_bf16 v[94:97], v[166:169], v[228:231], v[94:97]
	s_setprio 0
	s_setprio 1
	v_mfma_f32_16x16x32_bf16 v[74:77], v[170:173], v[186:189], v[74:77]
	v_mfma_f32_16x16x32_bf16 v[34:37], v[178:181], v[186:189], v[34:37]
	v_mfma_f32_16x16x32_bf16 v[62:65], v[170:173], v[208:211], v[62:65]
	v_mfma_f32_16x16x32_bf16 v[24:27], v[178:181], v[208:211], v[24:27]
	v_mfma_f32_16x16x32_bf16 v[54:57], v[170:173], v[216:219], v[54:57]
	v_mfma_f32_16x16x32_bf16 v[20:23], v[178:181], v[216:219], v[20:23]
	v_mfma_f32_16x16x32_bf16 v[38:41], v[170:173], v[224:227], v[38:41]
	v_mfma_f32_16x16x32_bf16 v[12:15], v[178:181], v[224:227], v[12:15]
	v_mfma_f32_16x16x32_bf16 v[74:77], v[174:177], v[204:207], v[74:77]
	v_mfma_f32_16x16x32_bf16 v[34:37], v[182:185], v[204:207], v[34:37]
	v_mfma_f32_16x16x32_bf16 v[62:65], v[174:177], v[212:215], v[62:65]
	v_mfma_f32_16x16x32_bf16 v[24:27], v[182:185], v[212:215], v[24:27]
	v_mfma_f32_16x16x32_bf16 v[54:57], v[174:177], v[220:223], v[54:57]
	v_mfma_f32_16x16x32_bf16 v[20:23], v[182:185], v[220:223], v[20:23]
	v_mfma_f32_16x16x32_bf16 v[38:41], v[174:177], v[228:231], v[38:41]
	v_mfma_f32_16x16x32_bf16 v[12:15], v[182:185], v[228:231], v[12:15]
	s_setprio 0
	s_barrier
; #define STAGE(bufoff, GB) do { const char* g_ = (GB); \
;         _Pragma("unroll") for (int i_ = 0; i_ < 2; ++i_) __builtin_amdgcn_global_load_lds((const unsigned*)(g_ + voff[i_]), (LAS3 unsigned*)(L + (bufoff) + stoff + i_ * 8192), 16, 0, 0); } while (0)
; #define LDA(dst, b, h) do { _Pragma("unroll") for (int m = 0; m < 4; ++m) _Pragma("unroll") for (int k = 0; k < 2; ++k) dst[m][k] = *(const LAS3 bf16x8*)(L + SA(b, h) + aoff + m * 2048 + k * 1024); } while (0)
; #define WAIT_V(n) asm volatile("s_waitcnt vmcnt(" #n ")" ::: "memory")
; #define WAIT_L(n) asm volatile("s_waitcnt lgkmcnt(" #n ")" ::: "memory")
; #define BAR __builtin_amdgcn_s_barrier()
; #define SCHED __builtin_amdgcn_sched_barrier(0)
; template <int EPI>
; DI void gemm_phase(const bf16_t* __restrict__ A, const bf16_t* __restrict__ Bt, const int K, const int N, const Params& p, const int layer_j, char* lds) {
;     ...
;             LDA(At, 1, 1); STAGE(SB(1, 0), b3); STAGE(SB(1, 1), b3 + hstep); STAGE(SA(1, 0), a3);
;             WAIT_V(8); WAIT_L(0); BAR; MMA(1, 0, At, B0); MMA(1, 1, At, B1); BAR; SCHED;
;         }
	v_readfirstlane_b32 s30, v148
	v_lshl_add_u64 v[136:137], v[136:137], 0, s[94:95]
	s_mov_b32 m0, s30
	v_readfirstlane_b32 s30, v149
	s_add_u32 s28, s28, 0x40080
	ds_read_b128 v[186:189], v139 offset:49152
	ds_read_b128 v[204:207], v139 offset:50176
	ds_read_b128 v[208:211], v139 offset:51200
	ds_read_b128 v[212:215], v139 offset:52224
	ds_read_b128 v[216:219], v139 offset:53248
	ds_read_b128 v[220:223], v139 offset:54272
	ds_read_b128 v[224:227], v139 offset:55296
	ds_read_b128 v[228:231], v139 offset:56320
	global_load_lds_dwordx4 v[136:137], off
	v_lshl_add_u64 v[136:137], v[190:191], 0, s[94:95]
	s_mov_b32 m0, s30
	s_addc_u32 s29, s29, 0
	v_readfirstlane_b32 s30, v152
	global_load_lds_dwordx4 v[136:137], off
	v_lshl_add_u64 v[136:137], s[28:29], 0, v[32:33]
	s_mov_b32 m0, s30
	s_nop 0
	global_load_lds_dwordx4 v[136:137], off
	v_lshl_add_u64 v[136:137], s[28:29], 0, v[130:131]
	v_readfirstlane_b32 s28, v153
	s_mov_b32 m0, s28
	v_readfirstlane_b32 s28, v150
	global_load_lds_dwordx4 v[136:137], off
	v_lshl_add_u64 v[136:137], v[194:195], 0, s[94:95]
	s_mov_b32 m0, s28
	v_readfirstlane_b32 s28, v151
	global_load_lds_dwordx4 v[136:137], off
	v_lshl_add_u64 v[136:137], v[232:233], 0, s[94:95]
	s_mov_b32 m0, s28
	s_nop 0
	global_load_lds_dwordx4 v[136:137], off
	s_waitcnt vmcnt(8)
	s_waitcnt lgkmcnt(0)
	s_barrier
	s_setprio 1
	s_waitcnt lgkmcnt(0)
	v_mfma_f32_16x16x32_bf16 v[98:101], v[154:157], v[186:189], v[98:101]
	v_mfma_f32_16x16x32_bf16 v[66:69], v[162:165], v[186:189], v[66:69]
	v_mfma_f32_16x16x32_bf16 v[90:93], v[154:157], v[208:211], v[90:93]
	v_mfma_f32_16x16x32_bf16 v[58:61], v[162:165], v[208:211], v[58:61]
	v_mfma_f32_16x16x32_bf16 v[86:89], v[154:157], v[216:219], v[86:89]
	v_mfma_f32_16x16x32_bf16 v[42:45], v[162:165], v[216:219], v[42:45]
	v_mfma_f32_16x16x32_bf16 v[70:73], v[154:157], v[224:227], v[70:73]
	v_mfma_f32_16x16x32_bf16 v[28:31], v[162:165], v[224:227], v[28:31]
	v_mfma_f32_16x16x32_bf16 v[98:101], v[158:161], v[204:207], v[98:101]
	v_mfma_f32_16x16x32_bf16 v[66:69], v[166:169], v[204:207], v[66:69]
	v_mfma_f32_16x16x32_bf16 v[90:93], v[158:161], v[212:215], v[90:93]
	v_mfma_f32_16x16x32_bf16 v[58:61], v[166:169], v[212:215], v[58:61]
	v_mfma_f32_16x16x32_bf16 v[86:89], v[158:161], v[220:223], v[86:89]
	v_mfma_f32_16x16x32_bf16 v[42:45], v[166:169], v[220:223], v[42:45]
	v_mfma_f32_16x16x32_bf16 v[70:73], v[158:161], v[228:231], v[70:73]
	v_mfma_f32_16x16x32_bf16 v[28:31], v[166:169], v[228:231], v[28:31]
	s_setprio 0
	s_setprio 1
	v_mfma_f32_16x16x32_bf16 v[16:19], v[170:173], v[186:189], v[16:19]
	v_mfma_f32_16x16x32_bf16 v[4:7], v[178:181], v[186:189], v[4:7]
	v_mfma_f32_16x16x32_bf16 v[8:11], v[170:173], v[208:211], v[8:11]
	v_mfma_f32_16x16x32_bf16 v[0:3], v[178:181], v[208:211], v[0:3]
	v_mfma_f32_16x16x32_bf16 v[78:81], v[170:173], v[216:219], v[78:81]
	v_mfma_f32_16x16x32_bf16 v[46:49], v[178:181], v[216:219], v[46:49]
	v_mfma_f32_16x16x32_bf16 v[82:85], v[170:173], v[224:227], v[82:85]
	v_mfma_f32_16x16x32_bf16 v[50:53], v[178:181], v[224:227], v[50:53]
	v_mfma_f32_16x16x32_bf16 v[16:19], v[174:177], v[204:207], v[16:19]
	v_mfma_f32_16x16x32_bf16 v[4:7], v[182:185], v[204:207], v[4:7]
	v_mfma_f32_16x16x32_bf16 v[8:11], v[174:177], v[212:215], v[8:11]
	v_mfma_f32_16x16x32_bf16 v[0:3], v[182:185], v[212:215], v[0:3]
	v_mfma_f32_16x16x32_bf16 v[78:81], v[174:177], v[220:223], v[78:81]
	v_mfma_f32_16x16x32_bf16 v[46:49], v[182:185], v[220:223], v[46:49]
	v_mfma_f32_16x16x32_bf16 v[82:85], v[174:177], v[228:231], v[82:85]
	v_mfma_f32_16x16x32_bf16 v[50:53], v[182:185], v[228:231], v[50:53]
	s_setprio 0
	s_barrier
	s_add_i32 s87, s87, 2
	s_add_u32 s26, s26, 0x100
	s_addc_u32 s27, s27, 0
	s_cmp_gt_u32 s87, 13
	s_cbranch_scc0 .LBB0_374
	s_branch .Latt_kloop_done

; #define STAGE(bufoff, GB) do { const char* g_ = (GB); \
;         _Pragma("unroll") for (int i_ = 0; i_ < 2; ++i_) __builtin_amdgcn_global_load_lds((const unsigned*)(g_ + voff[i_]), (LAS3 unsigned*)(L + (bufoff) + stoff + i_ * 8192), 16, 0, 0); } while (0)
; #define LDA(dst, b, h) do { _Pragma("unroll") for (int m = 0; m < 4; ++m) _Pragma("unroll") for (int k = 0; k < 2; ++k) dst[m][k] = *(const LAS3 bf16x8*)(L + SA(b, h) + aoff + m * 2048 + k * 1024); } while (0)
; #define WAIT_V(n) asm volatile("s_waitcnt vmcnt(" #n ")" ::: "memory")
; #define WAIT_L(n) asm volatile("s_waitcnt lgkmcnt(" #n ")" ::: "memory")
; #define BAR __builtin_amdgcn_s_barrier()
; #define SCHED __builtin_amdgcn_sched_barrier(0)
; template <int EPI>
; DI void gemm_phase(const bf16_t* __restrict__ A, const bf16_t* __restrict__ Bt, const int K, const int N, const Params& p, const int layer_j, char* lds) {
;     ...
;             WAIT_V(8); WAIT_L(0); BAR; MMA(0, 0, At, B0); MMA(0, 1, At, B1); BAR; SCHED;
;             LDA(At, 0, 1); STAGE(SB(0, 0), b2); STAGE(SB(0, 1), b2 + hstep); STAGE(SA(0, 0), a2);
;             WAIT_V(8); WAIT_L(0); BAR; MMA(1, 0, At, B0); MMA(1, 1, At, B1); BAR; SCHED;
.Lskipw_attns_0:
	s_waitcnt lgkmcnt(0)
	s_barrier
	s_setprio 1
	s_waitcnt lgkmcnt(0)
	s_nop 0
	v_mfma_f32_16x16x32_bf16 v[126:129], v[186:189], v[154:157], v[126:129]
	v_mfma_f32_16x16x32_bf16 v[110:113], v[186:189], v[162:165], v[110:113]
	v_mfma_f32_16x16x32_bf16 v[122:125], v[208:211], v[154:157], v[122:125]
	v_mfma_f32_16x16x32_bf16 v[106:109], v[208:211], v[162:165], v[106:109]
	v_mfma_f32_16x16x32_bf16 v[118:121], v[216:219], v[154:157], v[118:121]
	v_mfma_f32_16x16x32_bf16 v[102:105], v[216:219], v[162:165], v[102:105]
	v_mfma_f32_16x16x32_bf16 v[114:117], v[224:227], v[154:157], v[114:117]
	v_mfma_f32_16x16x32_bf16 v[94:97], v[224:227], v[162:165], v[94:97]
	v_mfma_f32_16x16x32_bf16 v[126:129], v[204:207], v[158:161], v[126:129]
	v_mfma_f32_16x16x32_bf16 v[110:113], v[204:207], v[166:169], v[110:113]
	v_mfma_f32_16x16x32_bf16 v[122:125], v[212:215], v[158:161], v[122:125]
	v_mfma_f32_16x16x32_bf16 v[106:109], v[212:215], v[166:169], v[106:109]
	v_mfma_f32_16x16x32_bf16 v[118:121], v[220:223], v[158:161], v[118:121]
	v_mfma_f32_16x16x32_bf16 v[102:105], v[220:223], v[166:169], v[102:105]
	v_mfma_f32_16x16x32_bf16 v[114:117], v[228:231], v[158:161], v[114:117]
	v_mfma_f32_16x16x32_bf16 v[94:97], v[228:231], v[166:169], v[94:97]
	s_setprio 0
	s_setprio 1
	v_mfma_f32_16x16x32_bf16 v[74:77], v[186:189], v[170:173], v[74:77]
	v_mfma_f32_16x16x32_bf16 v[34:37], v[186:189], v[178:181], v[34:37]
	v_mfma_f32_16x16x32_bf16 v[62:65], v[208:211], v[170:173], v[62:65]
	v_mfma_f32_16x16x32_bf16 v[24:27], v[208:211], v[178:181], v[24:27]
	v_mfma_f32_16x16x32_bf16 v[54:57], v[216:219], v[170:173], v[54:57]
	v_mfma_f32_16x16x32_bf16 v[20:23], v[216:219], v[178:181], v[20:23]
	v_mfma_f32_16x16x32_bf16 v[38:41], v[224:227], v[170:173], v[38:41]
	v_mfma_f32_16x16x32_bf16 v[12:15], v[224:227], v[178:181], v[12:15]
	v_mfma_f32_16x16x32_bf16 v[74:77], v[204:207], v[174:177], v[74:77]
	v_mfma_f32_16x16x32_bf16 v[34:37], v[204:207], v[182:185], v[34:37]
	v_mfma_f32_16x16x32_bf16 v[62:65], v[212:215], v[174:177], v[62:65]
	v_mfma_f32_16x16x32_bf16 v[24:27], v[212:215], v[182:185], v[24:27]
	v_mfma_f32_16x16x32_bf16 v[54:57], v[220:223], v[174:177], v[54:57]
	v_mfma_f32_16x16x32_bf16 v[20:23], v[220:223], v[182:185], v[20:23]
	v_mfma_f32_16x16x32_bf16 v[38:41], v[228:231], v[174:177], v[38:41]
	v_mfma_f32_16x16x32_bf16 v[12:15], v[228:231], v[182:185], v[12:15]
	s_setprio 0
	s_barrier
	v_readfirstlane_b32 s88, v141
	v_lshl_add_u64 v[136:137], s[28:29], 0, v[32:33]
	s_mov_b32 m0, s88
	v_readfirstlane_b32 s88, v142
	s_add_u32 vcc_lo, s28, 0x40000
	ds_read_b128 v[186:189], v139 offset:16384
	ds_read_b128 v[204:207], v139 offset:17408
	ds_read_b128 v[208:211], v139 offset:18432
	ds_read_b128 v[212:215], v139 offset:19456
	ds_read_b128 v[216:219], v139 offset:20480
	ds_read_b128 v[220:223], v139 offset:21504
	ds_read_b128 v[224:227], v139 offset:22528
	ds_read_b128 v[228:231], v139 offset:23552
	global_load_lds_dwordx4 v[136:137], off
	v_lshl_add_u64 v[190:191], s[28:29], 0, v[130:131]
	s_mov_b32 m0, s88
	s_addc_u32 vcc_hi, s29, 0
	v_readfirstlane_b32 s88, v143
	global_load_lds_dwordx4 v[190:191], off
	v_lshl_add_u64 v[194:195], vcc, 0, v[32:33]
	s_mov_b32 m0, s88
	v_readfirstlane_b32 s88, v144
	global_load_lds_dwordx4 v[194:195], off
	v_lshl_add_u64 v[194:195], vcc, 0, v[130:131]
	s_mov_b32 m0, s88
	v_readfirstlane_b32 s88, v138
	global_load_lds_dwordx4 v[194:195], off
	v_lshl_add_u64 v[194:195], s[30:31], 0, v[32:33]
	s_mov_b32 m0, s88
	v_readfirstlane_b32 s88, v145
	global_load_lds_dwordx4 v[194:195], off
	v_lshl_add_u64 v[232:233], s[30:31], 0, v[130:131]
	s_mov_b32 m0, s88
	s_nop 0
	global_load_lds_dwordx4 v[232:233], off
	s_cmp_eq_u32 s101, 0
	s_cbranch_scc1 .Lskipw_attns_1
	s_waitcnt vmcnt(8)
.Lskipw_attns_1:
	s_waitcnt lgkmcnt(0)
	s_barrier
	s_setprio 1
	s_waitcnt lgkmcnt(0)
	s_nop 0
	v_mfma_f32_16x16x32_bf16 v[98:101], v[186:189], v[154:157], v[98:101]
	v_mfma_f32_16x16x32_bf16 v[66:69], v[186:189], v[162:165], v[66:69]
	v_mfma_f32_16x16x32_bf16 v[90:93], v[208:211], v[154:157], v[90:93]
	v_mfma_f32_16x16x32_bf16 v[58:61], v[208:211], v[162:165], v[58:61]
	v_mfma_f32_16x16x32_bf16 v[86:89], v[216:219], v[154:157], v[86:89]
	v_mfma_f32_16x16x32_bf16 v[42:45], v[216:219], v[162:165], v[42:45]
	v_mfma_f32_16x16x32_bf16 v[70:73], v[224:227], v[154:157], v[70:73]
	v_mfma_f32_16x16x32_bf16 v[28:31], v[224:227], v[162:165], v[28:31]
	v_mfma_f32_16x16x32_bf16 v[98:101], v[204:207], v[158:161], v[98:101]
	v_mfma_f32_16x16x32_bf16 v[66:69], v[204:207], v[166:169], v[66:69]
	v_mfma_f32_16x16x32_bf16 v[90:93], v[212:215], v[158:161], v[90:93]
	v_mfma_f32_16x16x32_bf16 v[58:61], v[212:215], v[166:169], v[58:61]
	v_mfma_f32_16x16x32_bf16 v[86:89], v[220:223], v[158:161], v[86:89]
	v_mfma_f32_16x16x32_bf16 v[42:45], v[220:223], v[166:169], v[42:45]
	v_mfma_f32_16x16x32_bf16 v[70:73], v[228:231], v[158:161], v[70:73]
	v_mfma_f32_16x16x32_bf16 v[28:31], v[228:231], v[166:169], v[28:31]
	s_setprio 0
	s_setprio 1
	v_mfma_f32_16x16x32_bf16 v[16:19], v[186:189], v[170:173], v[16:19]
	v_mfma_f32_16x16x32_bf16 v[4:7], v[186:189], v[178:181], v[4:7]
	v_mfma_f32_16x16x32_bf16 v[8:11], v[208:211], v[170:173], v[8:11]
	v_mfma_f32_16x16x32_bf16 v[0:3], v[208:211], v[178:181], v[0:3]
	v_mfma_f32_16x16x32_bf16 v[78:81], v[216:219], v[170:173], v[78:81]
	v_mfma_f32_16x16x32_bf16 v[46:49], v[216:219], v[178:181], v[46:49]
	v_mfma_f32_16x16x32_bf16 v[82:85], v[224:227], v[170:173], v[82:85]
	v_mfma_f32_16x16x32_bf16 v[50:53], v[224:227], v[178:181], v[50:53]
	v_mfma_f32_16x16x32_bf16 v[16:19], v[204:207], v[174:177], v[16:19]
	v_mfma_f32_16x16x32_bf16 v[4:7], v[204:207], v[182:185], v[4:7]
	v_mfma_f32_16x16x32_bf16 v[8:11], v[212:215], v[174:177], v[8:11]
	v_mfma_f32_16x16x32_bf16 v[0:3], v[212:215], v[182:185], v[0:3]
	v_mfma_f32_16x16x32_bf16 v[78:81], v[220:223], v[174:177], v[78:81]
	v_mfma_f32_16x16x32_bf16 v[46:49], v[220:223], v[182:185], v[46:49]
	v_mfma_f32_16x16x32_bf16 v[82:85], v[228:231], v[174:177], v[82:85]
	v_mfma_f32_16x16x32_bf16 v[50:53], v[228:231], v[182:185], v[50:53]
	s_setprio 0
	s_barrier
; #define STAGE(bufoff, GB) do { const char* g_ = (GB); \
;         _Pragma("unroll") for (int i_ = 0; i_ < 2; ++i_) __builtin_amdgcn_global_load_lds((const unsigned*)(g_ + voff[i_]), (LAS3 unsigned*)(L + (bufoff) + stoff + i_ * 8192), 16, 0, 0); } while (0)
; #define LDA(dst, b, h) do { _Pragma("unroll") for (int m = 0; m < 4; ++m) _Pragma("unroll") for (int k = 0; k < 2; ++k) dst[m][k] = *(const LAS3 bf16x8*)(L + SA(b, h) + aoff + m * 2048 + k * 1024); } while (0)
; #define LDB(dst, b, h) do { _Pragma("unroll") for (int n = 0; n < 2; ++n) _Pragma("unroll") for (int k = 0; k < 2; ++k) dst[n][k] = *(const LAS3 bf16x8*)(L + SB(b, h) + boff + n * 2048 + k * 1024); } while (0)
; #define WAIT_V(n) asm volatile("s_waitcnt vmcnt(" #n ")" ::: "memory")
; #define WAIT_L(n) asm volatile("s_waitcnt lgkmcnt(" #n ")" ::: "memory")
; #define BAR __builtin_amdgcn_s_barrier()
; #define SCHED __builtin_amdgcn_sched_barrier(0)
; template <int EPI>
; DI void gemm_phase(const bf16_t* __restrict__ A, const bf16_t* __restrict__ Bt, const int K, const int N, const Params& p, const int layer_j, char* lds) {
;     ...
;             LDB(B0, 1, 0); LDB(B1, 1, 1); SCHED; LDA(At, 1, 0); STAGE(SA(0, 1), a2 + hstep);
;             WAIT_V(8); WAIT_L(0); BAR; MMA(0, 0, At, B0); MMA(0, 1, At, B1); BAR; SCHED;
	v_add_u32_e32 v166, 0x18000, v140
	v_add_u32_e32 v182, 0x1c000, v140
	ds_read_b128 v[154:157], v166
	ds_read_b128 v[158:161], v166 offset:1024
	ds_read_b128 v[162:165], v166 offset:2048
	ds_read_b128 v[166:169], v166 offset:3072
	ds_read_b128 v[170:173], v182
	ds_read_b128 v[174:177], v182 offset:1024
	ds_read_b128 v[178:181], v182 offset:2048
	ds_read_b128 v[182:185], v182 offset:3072
	s_add_u32 s30, s30, 0x40000
	s_addc_u32 s31, s31, 0
	v_readfirstlane_b32 s88, v146
	v_lshl_add_u64 v[234:235], s[30:31], 0, v[32:33]
	s_mov_b32 m0, s88
	ds_read_b128 v[186:189], v139 offset:32768
	ds_read_b128 v[204:207], v139 offset:33792
	ds_read_b128 v[208:211], v139 offset:34816
	ds_read_b128 v[212:215], v139 offset:35840
	ds_read_b128 v[216:219], v139 offset:36864
	ds_read_b128 v[220:223], v139 offset:37888
	ds_read_b128 v[224:227], v139 offset:38912
	ds_read_b128 v[228:231], v139 offset:39936
	global_load_lds_dwordx4 v[234:235], off
	v_lshl_add_u64 v[234:235], s[30:31], 0, v[130:131]
	v_readfirstlane_b32 s30, v147
	s_mov_b32 m0, s30
	s_nop 0
	global_load_lds_dwordx4 v[234:235], off
	s_waitcnt vmcnt(8)
	s_waitcnt lgkmcnt(0)
	s_barrier
	s_setprio 1
	s_waitcnt lgkmcnt(0)
	s_nop 0
	v_mfma_f32_16x16x32_bf16 v[126:129], v[186:189], v[154:157], v[126:129]
	v_mfma_f32_16x16x32_bf16 v[110:113], v[186:189], v[162:165], v[110:113]
	v_mfma_f32_16x16x32_bf16 v[122:125], v[208:211], v[154:157], v[122:125]
	v_mfma_f32_16x16x32_bf16 v[106:109], v[208:211], v[162:165], v[106:109]
	v_mfma_f32_16x16x32_bf16 v[118:121], v[216:219], v[154:157], v[118:121]
	v_mfma_f32_16x16x32_bf16 v[102:105], v[216:219], v[162:165], v[102:105]
	v_mfma_f32_16x16x32_bf16 v[114:117], v[224:227], v[154:157], v[114:117]
	v_mfma_f32_16x16x32_bf16 v[94:97], v[224:227], v[162:165], v[94:97]
	v_mfma_f32_16x16x32_bf16 v[126:129], v[204:207], v[158:161], v[126:129]
	v_mfma_f32_16x16x32_bf16 v[110:113], v[204:207], v[166:169], v[110:113]
	v_mfma_f32_16x16x32_bf16 v[122:125], v[212:215], v[158:161], v[122:125]
	v_mfma_f32_16x16x32_bf16 v[106:109], v[212:215], v[166:169], v[106:109]
	v_mfma_f32_16x16x32_bf16 v[118:121], v[220:223], v[158:161], v[118:121]
	v_mfma_f32_16x16x32_bf16 v[102:105], v[220:223], v[166:169], v[102:105]
	v_mfma_f32_16x16x32_bf16 v[114:117], v[228:231], v[158:161], v[114:117]
	v_mfma_f32_16x16x32_bf16 v[94:97], v[228:231], v[166:169], v[94:97]
	s_setprio 0
	s_setprio 1
	v_mfma_f32_16x16x32_bf16 v[74:77], v[186:189], v[170:173], v[74:77]
	v_mfma_f32_16x16x32_bf16 v[34:37], v[186:189], v[178:181], v[34:37]
	v_mfma_f32_16x16x32_bf16 v[62:65], v[208:211], v[170:173], v[62:65]
	v_mfma_f32_16x16x32_bf16 v[24:27], v[208:211], v[178:181], v[24:27]
	v_mfma_f32_16x16x32_bf16 v[54:57], v[216:219], v[170:173], v[54:57]
	v_mfma_f32_16x16x32_bf16 v[20:23], v[216:219], v[178:181], v[20:23]
	v_mfma_f32_16x16x32_bf16 v[38:41], v[224:227], v[170:173], v[38:41]
	v_mfma_f32_16x16x32_bf16 v[12:15], v[224:227], v[178:181], v[12:15]
	v_mfma_f32_16x16x32_bf16 v[74:77], v[204:207], v[174:177], v[74:77]
	v_mfma_f32_16x16x32_bf16 v[34:37], v[204:207], v[182:185], v[34:37]
	v_mfma_f32_16x16x32_bf16 v[62:65], v[212:215], v[174:177], v[62:65]
	v_mfma_f32_16x16x32_bf16 v[24:27], v[212:215], v[182:185], v[24:27]
	v_mfma_f32_16x16x32_bf16 v[54:57], v[220:223], v[174:177], v[54:57]
	v_mfma_f32_16x16x32_bf16 v[20:23], v[220:223], v[182:185], v[20:23]
	v_mfma_f32_16x16x32_bf16 v[38:41], v[228:231], v[174:177], v[38:41]
	v_mfma_f32_16x16x32_bf16 v[12:15], v[228:231], v[182:185], v[12:15]
	s_setprio 0
	s_barrier
; #define STAGE(bufoff, GB) do { const char* g_ = (GB); \
;         _Pragma("unroll") for (int i_ = 0; i_ < 2; ++i_) __builtin_amdgcn_global_load_lds((const unsigned*)(g_ + voff[i_]), (LAS3 unsigned*)(L + (bufoff) + stoff + i_ * 8192), 16, 0, 0); } while (0)
; #define LDA(dst, b, h) do { _Pragma("unroll") for (int m = 0; m < 4; ++m) _Pragma("unroll") for (int k = 0; k < 2; ++k) dst[m][k] = *(const LAS3 bf16x8*)(L + SA(b, h) + aoff + m * 2048 + k * 1024); } while (0)
; #define WAIT_V(n) asm volatile("s_waitcnt vmcnt(" #n ")" ::: "memory")
; #define WAIT_L(n) asm volatile("s_waitcnt lgkmcnt(" #n ")" ::: "memory")
; #define BAR __builtin_amdgcn_s_barrier()
; #define SCHED __builtin_amdgcn_sched_barrier(0)
; template <int EPI>
; DI void gemm_phase(const bf16_t* __restrict__ A, const bf16_t* __restrict__ Bt, const int K, const int N, const Params& p, const int layer_j, char* lds) {
;     ...
;             LDA(At, 1, 1); STAGE(SB(1, 0), b3); STAGE(SB(1, 1), b3 + hstep); STAGE(SA(1, 0), a3);
;             WAIT_V(8); WAIT_L(0); BAR; MMA(1, 0, At, B0); MMA(1, 1, At, B1); BAR; SCHED;
;         }
	v_readfirstlane_b32 s30, v148
	v_lshl_add_u64 v[136:137], v[136:137], 0, s[94:95]
	s_mov_b32 m0, s30
	v_readfirstlane_b32 s30, v149
	s_add_u32 s28, s28, 0x40080
	ds_read_b128 v[186:189], v139 offset:49152
	ds_read_b128 v[204:207], v139 offset:50176
	ds_read_b128 v[208:211], v139 offset:51200
	ds_read_b128 v[212:215], v139 offset:52224
	ds_read_b128 v[216:219], v139 offset:53248
	ds_read_b128 v[220:223], v139 offset:54272
	ds_read_b128 v[224:227], v139 offset:55296
	ds_read_b128 v[228:231], v139 offset:56320
	global_load_lds_dwordx4 v[136:137], off
	v_lshl_add_u64 v[136:137], v[190:191], 0, s[94:95]
	s_mov_b32 m0, s30
	s_addc_u32 s29, s29, 0
	v_readfirstlane_b32 s30, v152
	global_load_lds_dwordx4 v[136:137], off
	v_lshl_add_u64 v[136:137], s[28:29], 0, v[32:33]
	s_mov_b32 m0, s30
	s_nop 0
	global_load_lds_dwordx4 v[136:137], off
	v_lshl_add_u64 v[136:137], s[28:29], 0, v[130:131]
	v_readfirstlane_b32 s28, v153
	s_mov_b32 m0, s28
	v_readfirstlane_b32 s28, v150
	global_load_lds_dwordx4 v[136:137], off
	v_lshl_add_u64 v[136:137], v[194:195], 0, s[94:95]
	s_mov_b32 m0, s28
	v_readfirstlane_b32 s28, v151
	global_load_lds_dwordx4 v[136:137], off
	v_lshl_add_u64 v[136:137], v[232:233], 0, s[94:95]
	s_mov_b32 m0, s28
	s_nop 0
	global_load_lds_dwordx4 v[136:137], off
	s_waitcnt vmcnt(8)
	s_waitcnt lgkmcnt(0)
	s_barrier
	s_setprio 1
	s_waitcnt lgkmcnt(0)
	v_mfma_f32_16x16x32_bf16 v[98:101], v[186:189], v[154:157], v[98:101]
	v_mfma_f32_16x16x32_bf16 v[66:69], v[186:189], v[162:165], v[66:69]
	v_mfma_f32_16x16x32_bf16 v[90:93], v[208:211], v[154:157], v[90:93]
	v_mfma_f32_16x16x32_bf16 v[58:61], v[208:211], v[162:165], v[58:61]
	v_mfma_f32_16x16x32_bf16 v[86:89], v[216:219], v[154:157], v[86:89]
	v_mfma_f32_16x16x32_bf16 v[42:45], v[216:219], v[162:165], v[42:45]
	v_mfma_f32_16x16x32_bf16 v[70:73], v[224:227], v[154:157], v[70:73]
	v_mfma_f32_16x16x32_bf16 v[28:31], v[224:227], v[162:165], v[28:31]
	v_mfma_f32_16x16x32_bf16 v[98:101], v[204:207], v[158:161], v[98:101]
	v_mfma_f32_16x16x32_bf16 v[66:69], v[204:207], v[166:169], v[66:69]
	v_mfma_f32_16x16x32_bf16 v[90:93], v[212:215], v[158:161], v[90:93]
	v_mfma_f32_16x16x32_bf16 v[58:61], v[212:215], v[166:169], v[58:61]
	v_mfma_f32_16x16x32_bf16 v[86:89], v[220:223], v[158:161], v[86:89]
	v_mfma_f32_16x16x32_bf16 v[42:45], v[220:223], v[166:169], v[42:45]
	v_mfma_f32_16x16x32_bf16 v[70:73], v[228:231], v[158:161], v[70:73]
	v_mfma_f32_16x16x32_bf16 v[28:31], v[228:231], v[166:169], v[28:31]
	s_setprio 0
	s_setprio 1
	v_mfma_f32_16x16x32_bf16 v[16:19], v[186:189], v[170:173], v[16:19]
	v_mfma_f32_16x16x32_bf16 v[4:7], v[186:189], v[178:181], v[4:7]
	v_mfma_f32_16x16x32_bf16 v[8:11], v[208:211], v[170:173], v[8:11]
	v_mfma_f32_16x16x32_bf16 v[0:3], v[208:211], v[178:181], v[0:3]
	v_mfma_f32_16x16x32_bf16 v[78:81], v[216:219], v[170:173], v[78:81]
	v_mfma_f32_16x16x32_bf16 v[46:49], v[216:219], v[178:181], v[46:49]
	v_mfma_f32_16x16x32_bf16 v[82:85], v[224:227], v[170:173], v[82:85]
	v_mfma_f32_16x16x32_bf16 v[50:53], v[224:227], v[178:181], v[50:53]
	v_mfma_f32_16x16x32_bf16 v[16:19], v[204:207], v[174:177], v[16:19]
	v_mfma_f32_16x16x32_bf16 v[4:7], v[204:207], v[182:185], v[4:7]
	v_mfma_f32_16x16x32_bf16 v[8:11], v[212:215], v[174:177], v[8:11]
	v_mfma_f32_16x16x32_bf16 v[0:3], v[212:215], v[182:185], v[0:3]
	v_mfma_f32_16x16x32_bf16 v[78:81], v[220:223], v[174:177], v[78:81]
	v_mfma_f32_16x16x32_bf16 v[46:49], v[220:223], v[182:185], v[46:49]
	v_mfma_f32_16x16x32_bf16 v[82:85], v[228:231], v[174:177], v[82:85]
	v_mfma_f32_16x16x32_bf16 v[50:53], v[228:231], v[182:185], v[50:53]
	s_setprio 0
	s_barrier
	s_add_i32 s87, s87, 2
	s_add_u32 s26, s26, 0x100
	s_addc_u32 s27, s27, 0
	s_cmp_gt_u32 s87, 13
	s_cbranch_scc0 .Latt_kloop_ns
